# x2 + K-loop pacing barrier moved 2 MFMAs early with s_setprio 2 for the tail MFMAs (handoff overlap)
# baseline (speedup 1.0000x reference)
; #define PG8_STAGE(bufoff, gbase, voff) do { _Pragma("unroll") for (int _i = 0; _i < 2; ++_i) \
;         __builtin_amdgcn_global_load_lds((const unsigned*)((const char*)(gbase) + (voff)[_i]), (PG8_LAS unsigned*)(lds + (bufoff) + ldsw + _i * 8192), 16, 0, 0); } while (0)
; #define PG8_LDA(dst, b, h) do { _Pragma("unroll") for (int m = 0; m < 4; ++m) _Pragma("unroll") for (int k = 0; k < 2; ++k) dst[m][k] = *(const PG8_LAS bf16x8*)(lds + PG8_SA(b, h) + aoff + m * 2048 + k * 1024); } while (0)
; #define PG8_WAIT_V(n) asm volatile("s_waitcnt vmcnt(" #n ")" ::: "memory")
; #define PG8_WAIT_L(n) asm volatile("s_waitcnt lgkmcnt(" #n ")" ::: "memory")
; #define PG8_BAR __builtin_amdgcn_s_barrier()
; template <class Epi, class Sched, bool ALIGN_EPI = true, bool SP2 = true>
; __device__ __forceinline__ void gemm_phase(PG8_LAS unsigned char* lds, const Gemm g, const Sched& S, const Epi& E, const int tid) {
;     ...
;         for (int t = 0; t < nt; t += 2) {
;             const bool last = (t == nt - 2);
;             const char* a1 = cA + (size_t)(t + 1) * kstep;
;             const char* a2 = last ? nA : cA + (size_t)(t + 2) * kstep; const char* b2 = last ? nB : cB + (size_t)(t + 2) * kstep;
;             const char* a3 = a2 + kstep; const char* b3 = b2 + kstep;
;             if (last && has_next) S.a_ready(nxt);
;             if constexpr (SP2) {
;             PG8_LDB(B0, 0, 0); PG8_LDB(B1, 0, 1); PG8_SCHED; PG8_LDA(At, 0, 0); PG8_STAGE(PG8_SA(1, 1), a1 + hstepA, voffA);
;             PG8_WAIT_V(8); PG8_WAIT_L(0); PG8_BAR; PG8_MMA(0, 0, At, B0); PG8_MMA(0, 1, At, B1); PG8_BAR; PG8_SCHED;
;             PG8_LDA(At, 0, 1); PG8_STAGE(PG8_SB(0, 0), b2, voffB); PG8_STAGE(PG8_SB(0, 1), b2 + hstepB, voffB); PG8_STAGE(PG8_SA(0, 0), a2, voffA);
;             PG8_WAIT_V(8); PG8_WAIT_L(0); PG8_BAR; PG8_MMA(1, 0, At, B0); PG8_MMA(1, 1, At, B1); PG8_BAR; PG8_SCHED;
;             PG8_LDB(B0, 1, 0); PG8_LDB(B1, 1, 1); PG8_SCHED; PG8_LDA(At, 1, 0); PG8_STAGE(PG8_SA(0, 1), a2 + hstepA, voffA);
;             PG8_WAIT_V(8); PG8_WAIT_L(0); PG8_BAR; PG8_MMA(0, 0, At, B0); PG8_MMA(0, 1, At, B1); PG8_BAR; PG8_SCHED;
;             PG8_LDA(At, 1, 1); PG8_STAGE(PG8_SB(1, 0), b3, voffB); PG8_STAGE(PG8_SB(1, 1), b3 + hstepB, voffB); PG8_STAGE(PG8_SA(1, 0), a3, voffA);
;             PG8_WAIT_V(8); PG8_WAIT_L(0); PG8_BAR; PG8_MMA(1, 0, At, B0); PG8_MMA(1, 1, At, B1); PG8_BAR; PG8_SCHED;
.LBB0_381:
	s_add_u32 s25, s62, 0xfff80080
	s_addc_u32 s26, s63, -1
	s_add_i32 s27, 0, 0x10000
	s_cmp_eq_u32 s24, 28
	s_cselect_b32 s69, s18, s26
	s_cselect_b32 s68, s19, s25
	s_cselect_b32 s67, s20, s23
	s_cselect_b32 s66, s21, s22
	s_add_i32 s25, 0, 0x14000
	v_add_u32_e32 v158, s27, v163
	v_add_u32_e32 v165, s25, v163
	ds_read_b128 v[146:149], v158
	ds_read_b128 v[150:153], v158 offset:1024
	ds_read_b128 v[154:157], v158 offset:2048
	ds_read_b128 v[158:161], v158 offset:3072
	ds_read_b128 v[166:169], v165
	ds_read_b128 v[170:173], v165 offset:1024
	ds_read_b128 v[174:177], v165 offset:2048
	ds_read_b128 v[178:181], v165 offset:3072
	v_lshl_add_u64 v[200:201], s[62:63], 0, v[142:143]
	s_add_i32 m0, s82, 0xc000
	ds_read_b128 v[182:185], v164
	ds_read_b128 v[186:189], v164 offset:1024
	ds_read_b128 v[190:193], v164 offset:2048
	ds_read_b128 v[194:197], v164 offset:3072
	ds_read_b128 v[206:209], v164 offset:4096
	ds_read_b128 v[210:213], v164 offset:5120
	ds_read_b128 v[222:225], v164 offset:6144
	ds_read_b128 v[226:229], v164 offset:7168
	global_load_lds_dwordx4 v[200:201], off
	v_lshl_add_u64 v[200:201], s[62:63], 0, v[144:145]
	s_add_i32 m0, s82, 0xe000
	s_nop 0
	global_load_lds_dwordx4 v[200:201], off
	s_waitcnt vmcnt(8)
	s_waitcnt lgkmcnt(0)
	s_barrier
	s_setprio 1
	s_waitcnt lgkmcnt(0)
	v_mfma_f32_16x16x32_bf16 v[126:129], v[146:149], v[182:185], v[126:129]
	v_mfma_f32_16x16x32_bf16 v[126:129], v[150:153], v[186:189], v[126:129]
	v_mfma_f32_16x16x32_bf16 v[122:125], v[154:157], v[182:185], v[122:125]
	v_mfma_f32_16x16x32_bf16 v[122:125], v[158:161], v[186:189], v[122:125]
	v_mfma_f32_16x16x32_bf16 v[110:113], v[146:149], v[190:193], v[110:113]
	v_mfma_f32_16x16x32_bf16 v[110:113], v[150:153], v[194:197], v[110:113]
	v_mfma_f32_16x16x32_bf16 v[106:109], v[154:157], v[190:193], v[106:109]
	v_mfma_f32_16x16x32_bf16 v[106:109], v[158:161], v[194:197], v[106:109]
	v_mfma_f32_16x16x32_bf16 v[92:95], v[146:149], v[206:209], v[92:95]
	v_mfma_f32_16x16x32_bf16 v[92:95], v[150:153], v[210:213], v[92:95]
	v_mfma_f32_16x16x32_bf16 v[88:91], v[154:157], v[206:209], v[88:91]
	v_mfma_f32_16x16x32_bf16 v[88:91], v[158:161], v[210:213], v[88:91]
	v_mfma_f32_16x16x32_bf16 v[76:79], v[146:149], v[222:225], v[76:79]
	v_mfma_f32_16x16x32_bf16 v[76:79], v[150:153], v[226:229], v[76:79]
	v_mfma_f32_16x16x32_bf16 v[72:75], v[154:157], v[222:225], v[72:75]
	v_mfma_f32_16x16x32_bf16 v[72:75], v[158:161], v[226:229], v[72:75]
	s_setprio 0
	s_setprio 1
	v_mfma_f32_16x16x32_bf16 v[118:121], v[166:169], v[182:185], v[118:121]
	v_mfma_f32_16x16x32_bf16 v[118:121], v[170:173], v[186:189], v[118:121]
	v_mfma_f32_16x16x32_bf16 v[114:117], v[174:177], v[182:185], v[114:117]
	v_mfma_f32_16x16x32_bf16 v[114:117], v[178:181], v[186:189], v[114:117]
	v_mfma_f32_16x16x32_bf16 v[102:105], v[166:169], v[190:193], v[102:105]
	v_mfma_f32_16x16x32_bf16 v[102:105], v[170:173], v[194:197], v[102:105]
	v_mfma_f32_16x16x32_bf16 v[98:101], v[174:177], v[190:193], v[98:101]
	v_mfma_f32_16x16x32_bf16 v[98:101], v[178:181], v[194:197], v[98:101]
	v_mfma_f32_16x16x32_bf16 v[84:87], v[166:169], v[206:209], v[84:87]
	v_mfma_f32_16x16x32_bf16 v[84:87], v[170:173], v[210:213], v[84:87]
	v_mfma_f32_16x16x32_bf16 v[80:83], v[174:177], v[206:209], v[80:83]
	v_mfma_f32_16x16x32_bf16 v[80:83], v[178:181], v[210:213], v[80:83]
	v_mfma_f32_16x16x32_bf16 v[68:71], v[166:169], v[222:225], v[68:71]
	v_mfma_f32_16x16x32_bf16 v[68:71], v[170:173], v[226:229], v[68:71]
	s_setprio 2
	s_barrier
	v_mfma_f32_16x16x32_bf16 v[64:67], v[174:177], v[222:225], v[64:67]
	v_mfma_f32_16x16x32_bf16 v[64:67], v[178:181], v[226:229], v[64:67]
	s_setprio 0
	s_add_i32 s26, s27, s73
	v_lshl_add_u64 v[200:201], s[66:67], 0, v[132:133]
	s_mov_b32 m0, s26
	ds_read_b128 v[182:185], v164 offset:16384
	ds_read_b128 v[186:189], v164 offset:17408
	ds_read_b128 v[190:193], v164 offset:18432
	ds_read_b128 v[194:197], v164 offset:19456
	ds_read_b128 v[206:209], v164 offset:20480
	ds_read_b128 v[210:213], v164 offset:21504
	ds_read_b128 v[222:225], v164 offset:22528
	ds_read_b128 v[226:229], v164 offset:23552
	global_load_lds_dwordx4 v[200:201], off
	s_add_i32 m0, s26, 0x2000
	s_add_u32 s26, s66, 0x80000
	v_lshl_add_u64 v[202:203], s[66:67], 0, v[136:137]
	s_addc_u32 s27, s67, 0
	s_add_i32 s25, s25, s73
	global_load_lds_dwordx4 v[202:203], off
	v_lshl_add_u64 v[230:231], s[26:27], 0, v[132:133]
	s_mov_b32 m0, s25
	v_lshl_add_u64 v[232:233], s[68:69], 0, v[134:135]
	global_load_lds_dwordx4 v[230:231], off
	v_lshl_add_u64 v[230:231], s[26:27], 0, v[136:137]
	s_add_i32 m0, s25, 0x2000
	s_nop 0
	global_load_lds_dwordx4 v[230:231], off
	v_lshl_add_u64 v[230:231], s[68:69], 0, v[130:131]
	s_mov_b32 m0, s82
	s_nop 0
	global_load_lds_dwordx4 v[230:231], off
	s_mov_b32 m0, s83
	s_nop 0
	global_load_lds_dwordx4 v[232:233], off
	s_waitcnt vmcnt(8)
	s_waitcnt lgkmcnt(0)
	s_barrier
; #define PG8_STAGE(bufoff, gbase, voff) do { _Pragma("unroll") for (int _i = 0; _i < 2; ++_i) \
;         __builtin_amdgcn_global_load_lds((const unsigned*)((const char*)(gbase) + (voff)[_i]), (PG8_LAS unsigned*)(lds + (bufoff) + ldsw + _i * 8192), 16, 0, 0); } while (0)
; #define PG8_LDA(dst, b, h) do { _Pragma("unroll") for (int m = 0; m < 4; ++m) _Pragma("unroll") for (int k = 0; k < 2; ++k) dst[m][k] = *(const PG8_LAS bf16x8*)(lds + PG8_SA(b, h) + aoff + m * 2048 + k * 1024); } while (0)
; #define PG8_WAIT_V(n) asm volatile("s_waitcnt vmcnt(" #n ")" ::: "memory")
; #define PG8_WAIT_L(n) asm volatile("s_waitcnt lgkmcnt(" #n ")" ::: "memory")
; #define PG8_BAR __builtin_amdgcn_s_barrier()
; template <class Epi, class Sched, bool ALIGN_EPI = true, bool SP2 = true>
; __device__ __forceinline__ void gemm_phase(PG8_LAS unsigned char* lds, const Gemm g, const Sched& S, const Epi& E, const int tid) {
;     ...
;         for (int t = 0; t < nt; t += 2) {
;             const bool last = (t == nt - 2);
;             const char* a1 = cA + (size_t)(t + 1) * kstep;
;             const char* a2 = last ? nA : cA + (size_t)(t + 2) * kstep; const char* b2 = last ? nB : cB + (size_t)(t + 2) * kstep;
;             const char* a3 = a2 + kstep; const char* b3 = b2 + kstep;
;             if (last && has_next) S.a_ready(nxt);
;             if constexpr (SP2) {
;             PG8_LDB(B0, 0, 0); PG8_LDB(B1, 0, 1); PG8_SCHED; PG8_LDA(At, 0, 0); PG8_STAGE(PG8_SA(1, 1), a1 + hstepA, voffA);
;             PG8_WAIT_V(8); PG8_WAIT_L(0); PG8_BAR; PG8_MMA(0, 0, At, B0); PG8_MMA(0, 1, At, B1); PG8_BAR; PG8_SCHED;
;             PG8_LDA(At, 0, 1); PG8_STAGE(PG8_SB(0, 0), b2, voffB); PG8_STAGE(PG8_SB(0, 1), b2 + hstepB, voffB); PG8_STAGE(PG8_SA(0, 0), a2, voffA);
;             PG8_WAIT_V(8); PG8_WAIT_L(0); PG8_BAR; PG8_MMA(1, 0, At, B0); PG8_MMA(1, 1, At, B1); PG8_BAR; PG8_SCHED;
;             PG8_LDB(B0, 1, 0); PG8_LDB(B1, 1, 1); PG8_SCHED; PG8_LDA(At, 1, 0); PG8_STAGE(PG8_SA(0, 1), a2 + hstepA, voffA);
;             PG8_WAIT_V(8); PG8_WAIT_L(0); PG8_BAR; PG8_MMA(0, 0, At, B0); PG8_MMA(0, 1, At, B1); PG8_BAR; PG8_SCHED;
;             PG8_LDA(At, 1, 1); PG8_STAGE(PG8_SB(1, 0), b3, voffB); PG8_STAGE(PG8_SB(1, 1), b3 + hstepB, voffB); PG8_STAGE(PG8_SA(1, 0), a3, voffA);
;             PG8_WAIT_V(8); PG8_WAIT_L(0); PG8_BAR; PG8_MMA(1, 0, At, B0); PG8_MMA(1, 1, At, B1); PG8_BAR; PG8_SCHED;
	s_setprio 1
	s_waitcnt lgkmcnt(0)
	v_mfma_f32_16x16x32_bf16 v[60:63], v[146:149], v[182:185], v[60:63]
	v_mfma_f32_16x16x32_bf16 v[60:63], v[150:153], v[186:189], v[60:63]
	v_mfma_f32_16x16x32_bf16 v[56:59], v[154:157], v[182:185], v[56:59]
	v_mfma_f32_16x16x32_bf16 v[56:59], v[158:161], v[186:189], v[56:59]
	v_mfma_f32_16x16x32_bf16 v[44:47], v[146:149], v[190:193], v[44:47]
	v_mfma_f32_16x16x32_bf16 v[44:47], v[150:153], v[194:197], v[44:47]
	v_mfma_f32_16x16x32_bf16 v[40:43], v[154:157], v[190:193], v[40:43]
	v_mfma_f32_16x16x32_bf16 v[40:43], v[158:161], v[194:197], v[40:43]
	v_mfma_f32_16x16x32_bf16 v[28:31], v[146:149], v[206:209], v[28:31]
	v_mfma_f32_16x16x32_bf16 v[28:31], v[150:153], v[210:213], v[28:31]
	v_mfma_f32_16x16x32_bf16 v[24:27], v[154:157], v[206:209], v[24:27]
	v_mfma_f32_16x16x32_bf16 v[24:27], v[158:161], v[210:213], v[24:27]
	v_mfma_f32_16x16x32_bf16 v[12:15], v[146:149], v[222:225], v[12:15]
	v_mfma_f32_16x16x32_bf16 v[12:15], v[150:153], v[226:229], v[12:15]
	v_mfma_f32_16x16x32_bf16 v[8:11], v[154:157], v[222:225], v[8:11]
	v_mfma_f32_16x16x32_bf16 v[8:11], v[158:161], v[226:229], v[8:11]
	s_setprio 0
	s_setprio 1
	v_mfma_f32_16x16x32_bf16 v[52:55], v[166:169], v[182:185], v[52:55]
	v_mfma_f32_16x16x32_bf16 v[52:55], v[170:173], v[186:189], v[52:55]
	v_mfma_f32_16x16x32_bf16 v[48:51], v[174:177], v[182:185], v[48:51]
	v_mfma_f32_16x16x32_bf16 v[48:51], v[178:181], v[186:189], v[48:51]
	v_mfma_f32_16x16x32_bf16 v[36:39], v[166:169], v[190:193], v[36:39]
	v_mfma_f32_16x16x32_bf16 v[36:39], v[170:173], v[194:197], v[36:39]
	v_mfma_f32_16x16x32_bf16 v[32:35], v[174:177], v[190:193], v[32:35]
	v_mfma_f32_16x16x32_bf16 v[32:35], v[178:181], v[194:197], v[32:35]
	v_mfma_f32_16x16x32_bf16 v[20:23], v[166:169], v[206:209], v[20:23]
	v_mfma_f32_16x16x32_bf16 v[20:23], v[170:173], v[210:213], v[20:23]
	v_mfma_f32_16x16x32_bf16 v[16:19], v[174:177], v[206:209], v[16:19]
	v_mfma_f32_16x16x32_bf16 v[16:19], v[178:181], v[210:213], v[16:19]
	v_mfma_f32_16x16x32_bf16 v[4:7], v[166:169], v[222:225], v[4:7]
	v_mfma_f32_16x16x32_bf16 v[4:7], v[170:173], v[226:229], v[4:7]
	s_setprio 2
	s_barrier
	v_mfma_f32_16x16x32_bf16 v[0:3], v[174:177], v[222:225], v[0:3]
	v_mfma_f32_16x16x32_bf16 v[0:3], v[178:181], v[226:229], v[0:3]
	s_setprio 0
	s_add_i32 s25, 0, 0x18000
	s_add_i32 s28, 0, 0x1c000
	v_add_u32_e32 v158, s25, v163
	v_add_u32_e32 v165, s28, v163
	ds_read_b128 v[146:149], v158
	ds_read_b128 v[150:153], v158 offset:1024
	ds_read_b128 v[154:157], v158 offset:2048
	ds_read_b128 v[158:161], v158 offset:3072
	ds_read_b128 v[166:169], v165
	ds_read_b128 v[170:173], v165 offset:1024
	ds_read_b128 v[174:177], v165 offset:2048
	ds_read_b128 v[178:181], v165 offset:3072
	s_add_u32 s26, s68, 0x80000
	s_addc_u32 s27, s69, 0
	s_mov_b32 m0, s84
	v_lshl_add_u64 v[234:235], s[26:27], 0, v[130:131]
	ds_read_b128 v[182:185], v164 offset:32768
	ds_read_b128 v[186:189], v164 offset:33792
	ds_read_b128 v[190:193], v164 offset:34816
	ds_read_b128 v[194:197], v164 offset:35840
	ds_read_b128 v[206:209], v164 offset:36864
	ds_read_b128 v[210:213], v164 offset:37888
	ds_read_b128 v[222:225], v164 offset:38912
	ds_read_b128 v[226:229], v164 offset:39936
	global_load_lds_dwordx4 v[234:235], off
	v_lshl_add_u64 v[234:235], s[26:27], 0, v[134:135]
	s_mov_b32 m0, s85
	s_nop 0
	global_load_lds_dwordx4 v[234:235], off
	s_waitcnt vmcnt(8)
	s_waitcnt lgkmcnt(0)
	s_barrier
	s_setprio 1
	s_waitcnt lgkmcnt(0)
	v_mfma_f32_16x16x32_bf16 v[126:129], v[146:149], v[182:185], v[126:129]
	v_mfma_f32_16x16x32_bf16 v[126:129], v[150:153], v[186:189], v[126:129]
	v_mfma_f32_16x16x32_bf16 v[122:125], v[154:157], v[182:185], v[122:125]
	v_mfma_f32_16x16x32_bf16 v[122:125], v[158:161], v[186:189], v[122:125]
	v_mfma_f32_16x16x32_bf16 v[110:113], v[146:149], v[190:193], v[110:113]
	v_mfma_f32_16x16x32_bf16 v[110:113], v[150:153], v[194:197], v[110:113]
	v_mfma_f32_16x16x32_bf16 v[106:109], v[154:157], v[190:193], v[106:109]
	v_mfma_f32_16x16x32_bf16 v[106:109], v[158:161], v[194:197], v[106:109]
	v_mfma_f32_16x16x32_bf16 v[92:95], v[146:149], v[206:209], v[92:95]
	v_mfma_f32_16x16x32_bf16 v[92:95], v[150:153], v[210:213], v[92:95]
	v_mfma_f32_16x16x32_bf16 v[88:91], v[154:157], v[206:209], v[88:91]
	v_mfma_f32_16x16x32_bf16 v[88:91], v[158:161], v[210:213], v[88:91]
	v_mfma_f32_16x16x32_bf16 v[76:79], v[146:149], v[222:225], v[76:79]
	v_mfma_f32_16x16x32_bf16 v[76:79], v[150:153], v[226:229], v[76:79]
	v_mfma_f32_16x16x32_bf16 v[72:75], v[154:157], v[222:225], v[72:75]
	v_mfma_f32_16x16x32_bf16 v[72:75], v[158:161], v[226:229], v[72:75]
	s_setprio 0
	s_setprio 1
	v_mfma_f32_16x16x32_bf16 v[118:121], v[166:169], v[182:185], v[118:121]
	v_mfma_f32_16x16x32_bf16 v[118:121], v[170:173], v[186:189], v[118:121]
	v_mfma_f32_16x16x32_bf16 v[114:117], v[174:177], v[182:185], v[114:117]
	v_mfma_f32_16x16x32_bf16 v[114:117], v[178:181], v[186:189], v[114:117]
	v_mfma_f32_16x16x32_bf16 v[102:105], v[166:169], v[190:193], v[102:105]
	v_mfma_f32_16x16x32_bf16 v[102:105], v[170:173], v[194:197], v[102:105]
	v_mfma_f32_16x16x32_bf16 v[98:101], v[174:177], v[190:193], v[98:101]
	v_mfma_f32_16x16x32_bf16 v[98:101], v[178:181], v[194:197], v[98:101]
	v_mfma_f32_16x16x32_bf16 v[84:87], v[166:169], v[206:209], v[84:87]
	v_mfma_f32_16x16x32_bf16 v[84:87], v[170:173], v[210:213], v[84:87]
	v_mfma_f32_16x16x32_bf16 v[80:83], v[174:177], v[206:209], v[80:83]
	v_mfma_f32_16x16x32_bf16 v[80:83], v[178:181], v[210:213], v[80:83]
	v_mfma_f32_16x16x32_bf16 v[68:71], v[166:169], v[222:225], v[68:71]
	v_mfma_f32_16x16x32_bf16 v[68:71], v[170:173], v[226:229], v[68:71]
	s_setprio 2
	s_barrier
; #define PG8_STAGE(bufoff, gbase, voff) do { _Pragma("unroll") for (int _i = 0; _i < 2; ++_i) \
;         __builtin_amdgcn_global_load_lds((const unsigned*)((const char*)(gbase) + (voff)[_i]), (PG8_LAS unsigned*)(lds + (bufoff) + ldsw + _i * 8192), 16, 0, 0); } while (0)
; #define PG8_LDA(dst, b, h) do { _Pragma("unroll") for (int m = 0; m < 4; ++m) _Pragma("unroll") for (int k = 0; k < 2; ++k) dst[m][k] = *(const PG8_LAS bf16x8*)(lds + PG8_SA(b, h) + aoff + m * 2048 + k * 1024); } while (0)
; #define PG8_WAIT_V(n) asm volatile("s_waitcnt vmcnt(" #n ")" ::: "memory")
; #define PG8_WAIT_L(n) asm volatile("s_waitcnt lgkmcnt(" #n ")" ::: "memory")
; #define PG8_BAR __builtin_amdgcn_s_barrier()
; template <class Epi, class Sched, bool ALIGN_EPI = true, bool SP2 = true>
; __device__ __forceinline__ void gemm_phase(PG8_LAS unsigned char* lds, const Gemm g, const Sched& S, const Epi& E, const int tid) {
;     ...
;         for (int t = 0; t < nt; t += 2) {
;             const bool last = (t == nt - 2);
;             const char* a1 = cA + (size_t)(t + 1) * kstep;
;             const char* a2 = last ? nA : cA + (size_t)(t + 2) * kstep; const char* b2 = last ? nB : cB + (size_t)(t + 2) * kstep;
;             const char* a3 = a2 + kstep; const char* b3 = b2 + kstep;
;             if (last && has_next) S.a_ready(nxt);
;             if constexpr (SP2) {
;             PG8_LDB(B0, 0, 0); PG8_LDB(B1, 0, 1); PG8_SCHED; PG8_LDA(At, 0, 0); PG8_STAGE(PG8_SA(1, 1), a1 + hstepA, voffA);
;             PG8_WAIT_V(8); PG8_WAIT_L(0); PG8_BAR; PG8_MMA(0, 0, At, B0); PG8_MMA(0, 1, At, B1); PG8_BAR; PG8_SCHED;
;             PG8_LDA(At, 0, 1); PG8_STAGE(PG8_SB(0, 0), b2, voffB); PG8_STAGE(PG8_SB(0, 1), b2 + hstepB, voffB); PG8_STAGE(PG8_SA(0, 0), a2, voffA);
;             PG8_WAIT_V(8); PG8_WAIT_L(0); PG8_BAR; PG8_MMA(1, 0, At, B0); PG8_MMA(1, 1, At, B1); PG8_BAR; PG8_SCHED;
;             PG8_LDB(B0, 1, 0); PG8_LDB(B1, 1, 1); PG8_SCHED; PG8_LDA(At, 1, 0); PG8_STAGE(PG8_SA(0, 1), a2 + hstepA, voffA);
;             PG8_WAIT_V(8); PG8_WAIT_L(0); PG8_BAR; PG8_MMA(0, 0, At, B0); PG8_MMA(0, 1, At, B1); PG8_BAR; PG8_SCHED;
;             PG8_LDA(At, 1, 1); PG8_STAGE(PG8_SB(1, 0), b3, voffB); PG8_STAGE(PG8_SB(1, 1), b3 + hstepB, voffB); PG8_STAGE(PG8_SA(1, 0), a3, voffA);
;             PG8_WAIT_V(8); PG8_WAIT_L(0); PG8_BAR; PG8_MMA(1, 0, At, B0); PG8_MMA(1, 1, At, B1); PG8_BAR; PG8_SCHED;
	v_mfma_f32_16x16x32_bf16 v[64:67], v[174:177], v[222:225], v[64:67]
	v_mfma_f32_16x16x32_bf16 v[64:67], v[178:181], v[226:229], v[64:67]
	s_setprio 0
	s_add_i32 s25, s25, s73
	v_lshl_add_u64 v[200:201], v[200:201], 0, s[4:5]
	s_mov_b32 m0, s25
	ds_read_b128 v[182:185], v164 offset:49152
	ds_read_b128 v[186:189], v164 offset:50176
	ds_read_b128 v[190:193], v164 offset:51200
	ds_read_b128 v[194:197], v164 offset:52224
	ds_read_b128 v[206:209], v164 offset:53248
	ds_read_b128 v[210:213], v164 offset:54272
	ds_read_b128 v[222:225], v164 offset:55296
	ds_read_b128 v[226:229], v164 offset:56320
	global_load_lds_dwordx4 v[200:201], off
	s_add_i32 m0, s25, 0x2000
	s_add_u32 s26, s66, 0x80080
	v_lshl_add_u64 v[200:201], v[202:203], 0, s[4:5]
	s_addc_u32 s27, s67, 0
	s_add_i32 s25, s28, s73
	global_load_lds_dwordx4 v[200:201], off
	v_lshl_add_u64 v[200:201], s[26:27], 0, v[132:133]
	s_mov_b32 m0, s25
	s_nop 0
	global_load_lds_dwordx4 v[200:201], off
	v_lshl_add_u64 v[200:201], s[26:27], 0, v[136:137]
	s_add_i32 m0, s25, 0x2000
	s_nop 0
	global_load_lds_dwordx4 v[200:201], off
	v_lshl_add_u64 v[200:201], v[230:231], 0, s[4:5]
	s_mov_b32 m0, s88
	s_nop 0
	global_load_lds_dwordx4 v[200:201], off
	v_lshl_add_u64 v[200:201], v[232:233], 0, s[4:5]
	s_mov_b32 m0, s89
	s_nop 0
	global_load_lds_dwordx4 v[200:201], off
	s_waitcnt vmcnt(8)
	s_waitcnt lgkmcnt(0)
	s_barrier
	s_setprio 1
	s_waitcnt lgkmcnt(0)
	v_mfma_f32_16x16x32_bf16 v[60:63], v[146:149], v[182:185], v[60:63]
	v_mfma_f32_16x16x32_bf16 v[60:63], v[150:153], v[186:189], v[60:63]
	v_mfma_f32_16x16x32_bf16 v[56:59], v[154:157], v[182:185], v[56:59]
	v_mfma_f32_16x16x32_bf16 v[56:59], v[158:161], v[186:189], v[56:59]
	v_mfma_f32_16x16x32_bf16 v[44:47], v[146:149], v[190:193], v[44:47]
	v_mfma_f32_16x16x32_bf16 v[44:47], v[150:153], v[194:197], v[44:47]
	v_mfma_f32_16x16x32_bf16 v[40:43], v[154:157], v[190:193], v[40:43]
	v_mfma_f32_16x16x32_bf16 v[40:43], v[158:161], v[194:197], v[40:43]
	v_mfma_f32_16x16x32_bf16 v[28:31], v[146:149], v[206:209], v[28:31]
	v_mfma_f32_16x16x32_bf16 v[28:31], v[150:153], v[210:213], v[28:31]
	v_mfma_f32_16x16x32_bf16 v[24:27], v[154:157], v[206:209], v[24:27]
	v_mfma_f32_16x16x32_bf16 v[24:27], v[158:161], v[210:213], v[24:27]
	v_mfma_f32_16x16x32_bf16 v[12:15], v[146:149], v[222:225], v[12:15]
	v_mfma_f32_16x16x32_bf16 v[12:15], v[150:153], v[226:229], v[12:15]
	v_mfma_f32_16x16x32_bf16 v[8:11], v[154:157], v[222:225], v[8:11]
	v_mfma_f32_16x16x32_bf16 v[8:11], v[158:161], v[226:229], v[8:11]
	s_setprio 0
	s_setprio 1
	v_mfma_f32_16x16x32_bf16 v[52:55], v[166:169], v[182:185], v[52:55]
	v_mfma_f32_16x16x32_bf16 v[52:55], v[170:173], v[186:189], v[52:55]
	v_mfma_f32_16x16x32_bf16 v[48:51], v[174:177], v[182:185], v[48:51]
	v_mfma_f32_16x16x32_bf16 v[48:51], v[178:181], v[186:189], v[48:51]
	v_mfma_f32_16x16x32_bf16 v[36:39], v[166:169], v[190:193], v[36:39]
	v_mfma_f32_16x16x32_bf16 v[36:39], v[170:173], v[194:197], v[36:39]
	v_mfma_f32_16x16x32_bf16 v[32:35], v[174:177], v[190:193], v[32:35]
	v_mfma_f32_16x16x32_bf16 v[32:35], v[178:181], v[194:197], v[32:35]
	v_mfma_f32_16x16x32_bf16 v[20:23], v[166:169], v[206:209], v[20:23]
	v_mfma_f32_16x16x32_bf16 v[20:23], v[170:173], v[210:213], v[20:23]
	v_mfma_f32_16x16x32_bf16 v[16:19], v[174:177], v[206:209], v[16:19]
	v_mfma_f32_16x16x32_bf16 v[16:19], v[178:181], v[210:213], v[16:19]
	v_mfma_f32_16x16x32_bf16 v[4:7], v[166:169], v[222:225], v[4:7]
	v_mfma_f32_16x16x32_bf16 v[4:7], v[170:173], v[226:229], v[4:7]
	s_setprio 2
	s_barrier
	v_mfma_f32_16x16x32_bf16 v[0:3], v[174:177], v[222:225], v[0:3]
	v_mfma_f32_16x16x32_bf16 v[0:3], v[178:181], v[226:229], v[0:3]
	s_setprio 0
	s_add_i32 s24, s24, 2
	s_add_u32 s62, s62, 0x100
	s_addc_u32 s63, s63, 0
	s_add_u32 s22, s22, 0x100
	s_addc_u32 s23, s23, 0
	s_cmp_gt_u32 s24, 29
	s_cbranch_scc0 .LBB0_381
	s_and_b64 vcc, exec, s[52:53]
	s_cbranch_vccz .LBB0_384
	s_barrier

; #define PG8_STAGE(bufoff, gbase, voff) do { _Pragma("unroll") for (int _i = 0; _i < 2; ++_i) \
;         __builtin_amdgcn_global_load_lds((const unsigned*)((const char*)(gbase) + (voff)[_i]), (PG8_LAS unsigned*)(lds + (bufoff) + ldsw + _i * 8192), 16, 0, 0); } while (0)
; #define PG8_LDA(dst, b, h) do { _Pragma("unroll") for (int m = 0; m < 4; ++m) _Pragma("unroll") for (int k = 0; k < 2; ++k) dst[m][k] = *(const PG8_LAS bf16x8*)(lds + PG8_SA(b, h) + aoff + m * 2048 + k * 1024); } while (0)
; #define PG8_WAIT_V(n) asm volatile("s_waitcnt vmcnt(" #n ")" ::: "memory")
; #define PG8_WAIT_L(n) asm volatile("s_waitcnt lgkmcnt(" #n ")" ::: "memory")
; #define PG8_BAR __builtin_amdgcn_s_barrier()
; template <class Epi, class Sched, bool ALIGN_EPI = true, bool SP2 = true>
; __device__ __forceinline__ void gemm_phase(PG8_LAS unsigned char* lds, const Gemm g, const Sched& S, const Epi& E, const int tid) {
;     ...
;         for (int t = 0; t < nt; t += 2) {
;             const bool last = (t == nt - 2);
;             const char* a1 = cA + (size_t)(t + 1) * kstep;
;             const char* a2 = last ? nA : cA + (size_t)(t + 2) * kstep; const char* b2 = last ? nB : cB + (size_t)(t + 2) * kstep;
;             const char* a3 = a2 + kstep; const char* b3 = b2 + kstep;
;             if (last && has_next) S.a_ready(nxt);
;             if constexpr (SP2) {
;             PG8_LDB(B0, 0, 0); PG8_LDB(B1, 0, 1); PG8_SCHED; PG8_LDA(At, 0, 0); PG8_STAGE(PG8_SA(1, 1), a1 + hstepA, voffA);
;             PG8_WAIT_V(8); PG8_WAIT_L(0); PG8_BAR; PG8_MMA(0, 0, At, B0); PG8_MMA(0, 1, At, B1); PG8_BAR; PG8_SCHED;
;             PG8_LDA(At, 0, 1); PG8_STAGE(PG8_SB(0, 0), b2, voffB); PG8_STAGE(PG8_SB(0, 1), b2 + hstepB, voffB); PG8_STAGE(PG8_SA(0, 0), a2, voffA);
;             PG8_WAIT_V(8); PG8_WAIT_L(0); PG8_BAR; PG8_MMA(1, 0, At, B0); PG8_MMA(1, 1, At, B1); PG8_BAR; PG8_SCHED;
;             PG8_LDB(B0, 1, 0); PG8_LDB(B1, 1, 1); PG8_SCHED; PG8_LDA(At, 1, 0); PG8_STAGE(PG8_SA(0, 1), a2 + hstepA, voffA);
;             PG8_WAIT_V(8); PG8_WAIT_L(0); PG8_BAR; PG8_MMA(0, 0, At, B0); PG8_MMA(0, 1, At, B1); PG8_BAR; PG8_SCHED;
;             PG8_LDA(At, 1, 1); PG8_STAGE(PG8_SB(1, 0), b3, voffB); PG8_STAGE(PG8_SB(1, 1), b3 + hstepB, voffB); PG8_STAGE(PG8_SA(1, 0), a3, voffA);
;             PG8_WAIT_V(8); PG8_WAIT_L(0); PG8_BAR; PG8_MMA(1, 0, At, B0); PG8_MMA(1, 1, At, B1); PG8_BAR; PG8_SCHED;
.LBB0_700:
	s_add_i32 s29, s28, 2
	s_add_u32 s40, s42, 0x100
	s_addc_u32 s41, s43, 0
	s_add_i32 s48, 0, 0x10000
	s_cmp_eq_u32 s25, s28
	s_cselect_b32 s47, s71, s41
	s_cselect_b32 s46, s70, s40
	s_cselect_b32 s45, s73, s27
	s_cselect_b32 s44, s72, s26
	s_add_i32 s28, 0, 0x14000
	v_add_u32_e32 v162, s48, v152
	v_add_u32_e32 v178, s28, v152
	ds_read_b128 v[144:147], v162
	ds_read_b128 v[154:157], v162 offset:1024
	ds_read_b128 v[158:161], v162 offset:2048
	ds_read_b128 v[162:165], v162 offset:3072
	ds_read_b128 v[166:169], v178
	ds_read_b128 v[170:173], v178 offset:1024
	ds_read_b128 v[174:177], v178 offset:2048
	ds_read_b128 v[178:181], v178 offset:3072
	v_lshl_add_u64 v[200:201], s[42:43], 0, v[140:141]
	s_add_i32 m0, s89, 0xc000
	ds_read_b128 v[182:185], v153
	ds_read_b128 v[186:189], v153 offset:1024
	ds_read_b128 v[190:193], v153 offset:2048
	ds_read_b128 v[194:197], v153 offset:3072
	ds_read_b128 v[206:209], v153 offset:4096
	ds_read_b128 v[210:213], v153 offset:5120
	ds_read_b128 v[222:225], v153 offset:6144
	ds_read_b128 v[226:229], v153 offset:7168
	global_load_lds_dwordx4 v[200:201], off
	v_lshl_add_u64 v[200:201], s[42:43], 0, v[142:143]
	s_add_i32 m0, s89, 0xe000
	s_nop 0
	global_load_lds_dwordx4 v[200:201], off
	s_waitcnt vmcnt(8)
	s_waitcnt lgkmcnt(0)
	s_barrier
	s_setprio 1
	s_waitcnt lgkmcnt(0)
	v_mfma_f32_16x16x32_bf16 v[126:129], v[144:147], v[182:185], v[126:129]
	v_mfma_f32_16x16x32_bf16 v[126:129], v[154:157], v[186:189], v[126:129]
	v_mfma_f32_16x16x32_bf16 v[122:125], v[158:161], v[182:185], v[122:125]
	v_mfma_f32_16x16x32_bf16 v[122:125], v[162:165], v[186:189], v[122:125]
	v_mfma_f32_16x16x32_bf16 v[110:113], v[144:147], v[190:193], v[110:113]
	v_mfma_f32_16x16x32_bf16 v[110:113], v[154:157], v[194:197], v[110:113]
	v_mfma_f32_16x16x32_bf16 v[106:109], v[158:161], v[190:193], v[106:109]
	v_mfma_f32_16x16x32_bf16 v[106:109], v[162:165], v[194:197], v[106:109]
	v_mfma_f32_16x16x32_bf16 v[92:95], v[144:147], v[206:209], v[92:95]
	v_mfma_f32_16x16x32_bf16 v[92:95], v[154:157], v[210:213], v[92:95]
	v_mfma_f32_16x16x32_bf16 v[88:91], v[158:161], v[206:209], v[88:91]
	v_mfma_f32_16x16x32_bf16 v[88:91], v[162:165], v[210:213], v[88:91]
	v_mfma_f32_16x16x32_bf16 v[76:79], v[144:147], v[222:225], v[76:79]
	v_mfma_f32_16x16x32_bf16 v[76:79], v[154:157], v[226:229], v[76:79]
	v_mfma_f32_16x16x32_bf16 v[72:75], v[158:161], v[222:225], v[72:75]
	v_mfma_f32_16x16x32_bf16 v[72:75], v[162:165], v[226:229], v[72:75]
	s_setprio 0
	s_setprio 1
	v_mfma_f32_16x16x32_bf16 v[118:121], v[166:169], v[182:185], v[118:121]
	v_mfma_f32_16x16x32_bf16 v[118:121], v[170:173], v[186:189], v[118:121]
	v_mfma_f32_16x16x32_bf16 v[114:117], v[174:177], v[182:185], v[114:117]
	v_mfma_f32_16x16x32_bf16 v[114:117], v[178:181], v[186:189], v[114:117]
	v_mfma_f32_16x16x32_bf16 v[102:105], v[166:169], v[190:193], v[102:105]
	v_mfma_f32_16x16x32_bf16 v[102:105], v[170:173], v[194:197], v[102:105]
	v_mfma_f32_16x16x32_bf16 v[98:101], v[174:177], v[190:193], v[98:101]
	v_mfma_f32_16x16x32_bf16 v[98:101], v[178:181], v[194:197], v[98:101]
	v_mfma_f32_16x16x32_bf16 v[84:87], v[166:169], v[206:209], v[84:87]
	v_mfma_f32_16x16x32_bf16 v[84:87], v[170:173], v[210:213], v[84:87]
	v_mfma_f32_16x16x32_bf16 v[80:83], v[174:177], v[206:209], v[80:83]
	v_mfma_f32_16x16x32_bf16 v[80:83], v[178:181], v[210:213], v[80:83]
	v_mfma_f32_16x16x32_bf16 v[68:71], v[166:169], v[222:225], v[68:71]
	v_mfma_f32_16x16x32_bf16 v[68:71], v[170:173], v[226:229], v[68:71]
	s_setprio 2
	s_barrier
	v_mfma_f32_16x16x32_bf16 v[64:67], v[174:177], v[222:225], v[64:67]
	v_mfma_f32_16x16x32_bf16 v[64:67], v[178:181], v[226:229], v[64:67]
	s_setprio 0
	s_add_i32 s42, s48, s88
	v_lshl_add_u64 v[200:201], s[44:45], 0, v[132:133]
	s_mov_b32 m0, s42
	ds_read_b128 v[182:185], v153 offset:16384
	ds_read_b128 v[186:189], v153 offset:17408
	ds_read_b128 v[190:193], v153 offset:18432
	ds_read_b128 v[194:197], v153 offset:19456
	ds_read_b128 v[206:209], v153 offset:20480
	ds_read_b128 v[210:213], v153 offset:21504
	ds_read_b128 v[222:225], v153 offset:22528
	ds_read_b128 v[226:229], v153 offset:23552
	global_load_lds_dwordx4 v[200:201], off
	s_add_i32 m0, s42, 0x2000
	s_add_u32 s42, s44, 0x28000
	v_lshl_add_u64 v[202:203], s[44:45], 0, v[136:137]
	s_addc_u32 s43, s45, 0
	s_add_i32 s28, s28, s88
	global_load_lds_dwordx4 v[202:203], off
	v_lshl_add_u64 v[230:231], s[42:43], 0, v[132:133]
	s_mov_b32 m0, s28
	v_lshl_add_u64 v[232:233], s[46:47], 0, v[134:135]
	global_load_lds_dwordx4 v[230:231], off
	v_lshl_add_u64 v[230:231], s[42:43], 0, v[136:137]
	s_add_i32 m0, s28, 0x2000
	s_nop 0
	global_load_lds_dwordx4 v[230:231], off
	v_lshl_add_u64 v[230:231], s[46:47], 0, v[130:131]
	s_mov_b32 m0, s89
	s_nop 0
	global_load_lds_dwordx4 v[230:231], off
	s_mov_b32 m0, s90
	s_nop 0
	global_load_lds_dwordx4 v[232:233], off
	s_waitcnt vmcnt(8)
	s_waitcnt lgkmcnt(0)
	s_barrier
; #define PG8_STAGE(bufoff, gbase, voff) do { _Pragma("unroll") for (int _i = 0; _i < 2; ++_i) \
;         __builtin_amdgcn_global_load_lds((const unsigned*)((const char*)(gbase) + (voff)[_i]), (PG8_LAS unsigned*)(lds + (bufoff) + ldsw + _i * 8192), 16, 0, 0); } while (0)
; #define PG8_LDA(dst, b, h) do { _Pragma("unroll") for (int m = 0; m < 4; ++m) _Pragma("unroll") for (int k = 0; k < 2; ++k) dst[m][k] = *(const PG8_LAS bf16x8*)(lds + PG8_SA(b, h) + aoff + m * 2048 + k * 1024); } while (0)
; #define PG8_WAIT_V(n) asm volatile("s_waitcnt vmcnt(" #n ")" ::: "memory")
; #define PG8_WAIT_L(n) asm volatile("s_waitcnt lgkmcnt(" #n ")" ::: "memory")
; #define PG8_BAR __builtin_amdgcn_s_barrier()
; template <class Epi, class Sched, bool ALIGN_EPI = true, bool SP2 = true>
; __device__ __forceinline__ void gemm_phase(PG8_LAS unsigned char* lds, const Gemm g, const Sched& S, const Epi& E, const int tid) {
;     ...
;         for (int t = 0; t < nt; t += 2) {
;             const bool last = (t == nt - 2);
;             const char* a1 = cA + (size_t)(t + 1) * kstep;
;             const char* a2 = last ? nA : cA + (size_t)(t + 2) * kstep; const char* b2 = last ? nB : cB + (size_t)(t + 2) * kstep;
;             const char* a3 = a2 + kstep; const char* b3 = b2 + kstep;
;             if (last && has_next) S.a_ready(nxt);
;             if constexpr (SP2) {
;             PG8_LDB(B0, 0, 0); PG8_LDB(B1, 0, 1); PG8_SCHED; PG8_LDA(At, 0, 0); PG8_STAGE(PG8_SA(1, 1), a1 + hstepA, voffA);
;             PG8_WAIT_V(8); PG8_WAIT_L(0); PG8_BAR; PG8_MMA(0, 0, At, B0); PG8_MMA(0, 1, At, B1); PG8_BAR; PG8_SCHED;
;             PG8_LDA(At, 0, 1); PG8_STAGE(PG8_SB(0, 0), b2, voffB); PG8_STAGE(PG8_SB(0, 1), b2 + hstepB, voffB); PG8_STAGE(PG8_SA(0, 0), a2, voffA);
;             PG8_WAIT_V(8); PG8_WAIT_L(0); PG8_BAR; PG8_MMA(1, 0, At, B0); PG8_MMA(1, 1, At, B1); PG8_BAR; PG8_SCHED;
;             PG8_LDB(B0, 1, 0); PG8_LDB(B1, 1, 1); PG8_SCHED; PG8_LDA(At, 1, 0); PG8_STAGE(PG8_SA(0, 1), a2 + hstepA, voffA);
;             PG8_WAIT_V(8); PG8_WAIT_L(0); PG8_BAR; PG8_MMA(0, 0, At, B0); PG8_MMA(0, 1, At, B1); PG8_BAR; PG8_SCHED;
;             PG8_LDA(At, 1, 1); PG8_STAGE(PG8_SB(1, 0), b3, voffB); PG8_STAGE(PG8_SB(1, 1), b3 + hstepB, voffB); PG8_STAGE(PG8_SA(1, 0), a3, voffA);
;             PG8_WAIT_V(8); PG8_WAIT_L(0); PG8_BAR; PG8_MMA(1, 0, At, B0); PG8_MMA(1, 1, At, B1); PG8_BAR; PG8_SCHED;
	s_setprio 1
	s_waitcnt lgkmcnt(0)
	v_mfma_f32_16x16x32_bf16 v[60:63], v[144:147], v[182:185], v[60:63]
	v_mfma_f32_16x16x32_bf16 v[60:63], v[154:157], v[186:189], v[60:63]
	v_mfma_f32_16x16x32_bf16 v[56:59], v[158:161], v[182:185], v[56:59]
	v_mfma_f32_16x16x32_bf16 v[56:59], v[162:165], v[186:189], v[56:59]
	v_mfma_f32_16x16x32_bf16 v[44:47], v[144:147], v[190:193], v[44:47]
	v_mfma_f32_16x16x32_bf16 v[44:47], v[154:157], v[194:197], v[44:47]
	v_mfma_f32_16x16x32_bf16 v[40:43], v[158:161], v[190:193], v[40:43]
	v_mfma_f32_16x16x32_bf16 v[40:43], v[162:165], v[194:197], v[40:43]
	v_mfma_f32_16x16x32_bf16 v[28:31], v[144:147], v[206:209], v[28:31]
	v_mfma_f32_16x16x32_bf16 v[28:31], v[154:157], v[210:213], v[28:31]
	v_mfma_f32_16x16x32_bf16 v[24:27], v[158:161], v[206:209], v[24:27]
	v_mfma_f32_16x16x32_bf16 v[24:27], v[162:165], v[210:213], v[24:27]
	v_mfma_f32_16x16x32_bf16 v[12:15], v[144:147], v[222:225], v[12:15]
	v_mfma_f32_16x16x32_bf16 v[12:15], v[154:157], v[226:229], v[12:15]
	v_mfma_f32_16x16x32_bf16 v[8:11], v[158:161], v[222:225], v[8:11]
	v_mfma_f32_16x16x32_bf16 v[8:11], v[162:165], v[226:229], v[8:11]
	s_setprio 0
	s_setprio 1
	v_mfma_f32_16x16x32_bf16 v[52:55], v[166:169], v[182:185], v[52:55]
	v_mfma_f32_16x16x32_bf16 v[52:55], v[170:173], v[186:189], v[52:55]
	v_mfma_f32_16x16x32_bf16 v[48:51], v[174:177], v[182:185], v[48:51]
	v_mfma_f32_16x16x32_bf16 v[48:51], v[178:181], v[186:189], v[48:51]
	v_mfma_f32_16x16x32_bf16 v[36:39], v[166:169], v[190:193], v[36:39]
	v_mfma_f32_16x16x32_bf16 v[36:39], v[170:173], v[194:197], v[36:39]
	v_mfma_f32_16x16x32_bf16 v[32:35], v[174:177], v[190:193], v[32:35]
	v_mfma_f32_16x16x32_bf16 v[32:35], v[178:181], v[194:197], v[32:35]
	v_mfma_f32_16x16x32_bf16 v[20:23], v[166:169], v[206:209], v[20:23]
	v_mfma_f32_16x16x32_bf16 v[20:23], v[170:173], v[210:213], v[20:23]
	v_mfma_f32_16x16x32_bf16 v[16:19], v[174:177], v[206:209], v[16:19]
	v_mfma_f32_16x16x32_bf16 v[16:19], v[178:181], v[210:213], v[16:19]
	v_mfma_f32_16x16x32_bf16 v[4:7], v[166:169], v[222:225], v[4:7]
	v_mfma_f32_16x16x32_bf16 v[4:7], v[170:173], v[226:229], v[4:7]
	s_setprio 2
	s_barrier
	v_mfma_f32_16x16x32_bf16 v[0:3], v[174:177], v[222:225], v[0:3]
	v_mfma_f32_16x16x32_bf16 v[0:3], v[178:181], v[226:229], v[0:3]
	s_setprio 0
	s_add_i32 s28, 0, 0x18000
	s_add_i32 s48, 0, 0x1c000
	v_add_u32_e32 v162, s28, v152
	v_add_u32_e32 v178, s48, v152
	ds_read_b128 v[144:147], v162
	ds_read_b128 v[154:157], v162 offset:1024
	ds_read_b128 v[158:161], v162 offset:2048
	ds_read_b128 v[162:165], v162 offset:3072
	ds_read_b128 v[166:169], v178
	ds_read_b128 v[170:173], v178 offset:1024
	ds_read_b128 v[174:177], v178 offset:2048
	ds_read_b128 v[178:181], v178 offset:3072
	s_add_u32 s42, s46, 0x150000
	s_addc_u32 s43, s47, 0
	s_mov_b32 m0, s91
	v_lshl_add_u64 v[234:235], s[42:43], 0, v[130:131]
	ds_read_b128 v[182:185], v153 offset:32768
	ds_read_b128 v[186:189], v153 offset:33792
	ds_read_b128 v[190:193], v153 offset:34816
	ds_read_b128 v[194:197], v153 offset:35840
	ds_read_b128 v[206:209], v153 offset:36864
	ds_read_b128 v[210:213], v153 offset:37888
	ds_read_b128 v[222:225], v153 offset:38912
	ds_read_b128 v[226:229], v153 offset:39936
	global_load_lds_dwordx4 v[234:235], off
	v_lshl_add_u64 v[234:235], s[42:43], 0, v[134:135]
	s_mov_b32 m0, s80
	s_nop 0
	global_load_lds_dwordx4 v[234:235], off
	s_waitcnt vmcnt(8)
	s_waitcnt lgkmcnt(0)
	s_barrier
	s_setprio 1
	s_waitcnt lgkmcnt(0)
	v_mfma_f32_16x16x32_bf16 v[126:129], v[144:147], v[182:185], v[126:129]
	v_mfma_f32_16x16x32_bf16 v[126:129], v[154:157], v[186:189], v[126:129]
	v_mfma_f32_16x16x32_bf16 v[122:125], v[158:161], v[182:185], v[122:125]
	v_mfma_f32_16x16x32_bf16 v[122:125], v[162:165], v[186:189], v[122:125]
	v_mfma_f32_16x16x32_bf16 v[110:113], v[144:147], v[190:193], v[110:113]
	v_mfma_f32_16x16x32_bf16 v[110:113], v[154:157], v[194:197], v[110:113]
	v_mfma_f32_16x16x32_bf16 v[106:109], v[158:161], v[190:193], v[106:109]
	v_mfma_f32_16x16x32_bf16 v[106:109], v[162:165], v[194:197], v[106:109]
	v_mfma_f32_16x16x32_bf16 v[92:95], v[144:147], v[206:209], v[92:95]
	v_mfma_f32_16x16x32_bf16 v[92:95], v[154:157], v[210:213], v[92:95]
	v_mfma_f32_16x16x32_bf16 v[88:91], v[158:161], v[206:209], v[88:91]
	v_mfma_f32_16x16x32_bf16 v[88:91], v[162:165], v[210:213], v[88:91]
	v_mfma_f32_16x16x32_bf16 v[76:79], v[144:147], v[222:225], v[76:79]
	v_mfma_f32_16x16x32_bf16 v[76:79], v[154:157], v[226:229], v[76:79]
	v_mfma_f32_16x16x32_bf16 v[72:75], v[158:161], v[222:225], v[72:75]
	v_mfma_f32_16x16x32_bf16 v[72:75], v[162:165], v[226:229], v[72:75]
	s_setprio 0
	s_setprio 1
	v_mfma_f32_16x16x32_bf16 v[118:121], v[166:169], v[182:185], v[118:121]
	v_mfma_f32_16x16x32_bf16 v[118:121], v[170:173], v[186:189], v[118:121]
	v_mfma_f32_16x16x32_bf16 v[114:117], v[174:177], v[182:185], v[114:117]
	v_mfma_f32_16x16x32_bf16 v[114:117], v[178:181], v[186:189], v[114:117]
	v_mfma_f32_16x16x32_bf16 v[102:105], v[166:169], v[190:193], v[102:105]
	v_mfma_f32_16x16x32_bf16 v[102:105], v[170:173], v[194:197], v[102:105]
	v_mfma_f32_16x16x32_bf16 v[98:101], v[174:177], v[190:193], v[98:101]
	v_mfma_f32_16x16x32_bf16 v[98:101], v[178:181], v[194:197], v[98:101]
	v_mfma_f32_16x16x32_bf16 v[84:87], v[166:169], v[206:209], v[84:87]
	v_mfma_f32_16x16x32_bf16 v[84:87], v[170:173], v[210:213], v[84:87]
	v_mfma_f32_16x16x32_bf16 v[80:83], v[174:177], v[206:209], v[80:83]
	v_mfma_f32_16x16x32_bf16 v[80:83], v[178:181], v[210:213], v[80:83]
	v_mfma_f32_16x16x32_bf16 v[68:71], v[166:169], v[222:225], v[68:71]
	v_mfma_f32_16x16x32_bf16 v[68:71], v[170:173], v[226:229], v[68:71]
	s_setprio 2
	s_barrier
; #define PG8_STAGE(bufoff, gbase, voff) do { _Pragma("unroll") for (int _i = 0; _i < 2; ++_i) \
;         __builtin_amdgcn_global_load_lds((const unsigned*)((const char*)(gbase) + (voff)[_i]), (PG8_LAS unsigned*)(lds + (bufoff) + ldsw + _i * 8192), 16, 0, 0); } while (0)
; #define PG8_LDA(dst, b, h) do { _Pragma("unroll") for (int m = 0; m < 4; ++m) _Pragma("unroll") for (int k = 0; k < 2; ++k) dst[m][k] = *(const PG8_LAS bf16x8*)(lds + PG8_SA(b, h) + aoff + m * 2048 + k * 1024); } while (0)
; #define PG8_WAIT_V(n) asm volatile("s_waitcnt vmcnt(" #n ")" ::: "memory")
; #define PG8_WAIT_L(n) asm volatile("s_waitcnt lgkmcnt(" #n ")" ::: "memory")
; #define PG8_BAR __builtin_amdgcn_s_barrier()
; template <class Epi, class Sched, bool ALIGN_EPI = true, bool SP2 = true>
; __device__ __forceinline__ void gemm_phase(PG8_LAS unsigned char* lds, const Gemm g, const Sched& S, const Epi& E, const int tid) {
;     ...
;         for (int t = 0; t < nt; t += 2) {
;             const bool last = (t == nt - 2);
;             const char* a1 = cA + (size_t)(t + 1) * kstep;
;             const char* a2 = last ? nA : cA + (size_t)(t + 2) * kstep; const char* b2 = last ? nB : cB + (size_t)(t + 2) * kstep;
;             const char* a3 = a2 + kstep; const char* b3 = b2 + kstep;
;             if (last && has_next) S.a_ready(nxt);
;             if constexpr (SP2) {
;             PG8_LDB(B0, 0, 0); PG8_LDB(B1, 0, 1); PG8_SCHED; PG8_LDA(At, 0, 0); PG8_STAGE(PG8_SA(1, 1), a1 + hstepA, voffA);
;             PG8_WAIT_V(8); PG8_WAIT_L(0); PG8_BAR; PG8_MMA(0, 0, At, B0); PG8_MMA(0, 1, At, B1); PG8_BAR; PG8_SCHED;
;             PG8_LDA(At, 0, 1); PG8_STAGE(PG8_SB(0, 0), b2, voffB); PG8_STAGE(PG8_SB(0, 1), b2 + hstepB, voffB); PG8_STAGE(PG8_SA(0, 0), a2, voffA);
;             PG8_WAIT_V(8); PG8_WAIT_L(0); PG8_BAR; PG8_MMA(1, 0, At, B0); PG8_MMA(1, 1, At, B1); PG8_BAR; PG8_SCHED;
;             PG8_LDB(B0, 1, 0); PG8_LDB(B1, 1, 1); PG8_SCHED; PG8_LDA(At, 1, 0); PG8_STAGE(PG8_SA(0, 1), a2 + hstepA, voffA);
;             PG8_WAIT_V(8); PG8_WAIT_L(0); PG8_BAR; PG8_MMA(0, 0, At, B0); PG8_MMA(0, 1, At, B1); PG8_BAR; PG8_SCHED;
;             PG8_LDA(At, 1, 1); PG8_STAGE(PG8_SB(1, 0), b3, voffB); PG8_STAGE(PG8_SB(1, 1), b3 + hstepB, voffB); PG8_STAGE(PG8_SA(1, 0), a3, voffA);
;             PG8_WAIT_V(8); PG8_WAIT_L(0); PG8_BAR; PG8_MMA(1, 0, At, B0); PG8_MMA(1, 1, At, B1); PG8_BAR; PG8_SCHED;
	v_mfma_f32_16x16x32_bf16 v[64:67], v[174:177], v[222:225], v[64:67]
	v_mfma_f32_16x16x32_bf16 v[64:67], v[178:181], v[226:229], v[64:67]
	s_setprio 0
	s_add_i32 s28, s28, s88
	v_lshl_add_u64 v[200:201], v[200:201], 0, s[4:5]
	s_mov_b32 m0, s28
	ds_read_b128 v[182:185], v153 offset:49152
	ds_read_b128 v[186:189], v153 offset:50176
	ds_read_b128 v[190:193], v153 offset:51200
	ds_read_b128 v[194:197], v153 offset:52224
	ds_read_b128 v[206:209], v153 offset:53248
	ds_read_b128 v[210:213], v153 offset:54272
	ds_read_b128 v[222:225], v153 offset:55296
	ds_read_b128 v[226:229], v153 offset:56320
	global_load_lds_dwordx4 v[200:201], off
	s_add_i32 m0, s28, 0x2000
	s_add_u32 s42, s44, 0x28080
	v_lshl_add_u64 v[200:201], v[202:203], 0, s[4:5]
	s_addc_u32 s43, s45, 0
	s_add_i32 s28, s48, s88
	global_load_lds_dwordx4 v[200:201], off
	v_lshl_add_u64 v[200:201], s[42:43], 0, v[132:133]
	s_mov_b32 m0, s28
	s_nop 0
	global_load_lds_dwordx4 v[200:201], off
	v_lshl_add_u64 v[200:201], s[42:43], 0, v[136:137]
	s_add_i32 m0, s28, 0x2000
	s_nop 0
	global_load_lds_dwordx4 v[200:201], off
	v_lshl_add_u64 v[200:201], v[230:231], 0, s[4:5]
	s_mov_b32 m0, s56
	s_nop 0
	global_load_lds_dwordx4 v[200:201], off
	v_lshl_add_u64 v[200:201], v[232:233], 0, s[4:5]
	s_mov_b32 m0, s57
	s_nop 0
	global_load_lds_dwordx4 v[200:201], off
	s_waitcnt vmcnt(8)
	s_waitcnt lgkmcnt(0)
	s_barrier
	s_setprio 1
	s_waitcnt lgkmcnt(0)
	v_mfma_f32_16x16x32_bf16 v[60:63], v[144:147], v[182:185], v[60:63]
	v_mfma_f32_16x16x32_bf16 v[60:63], v[154:157], v[186:189], v[60:63]
	v_mfma_f32_16x16x32_bf16 v[56:59], v[158:161], v[182:185], v[56:59]
	v_mfma_f32_16x16x32_bf16 v[56:59], v[162:165], v[186:189], v[56:59]
	v_mfma_f32_16x16x32_bf16 v[44:47], v[144:147], v[190:193], v[44:47]
	v_mfma_f32_16x16x32_bf16 v[44:47], v[154:157], v[194:197], v[44:47]
	v_mfma_f32_16x16x32_bf16 v[40:43], v[158:161], v[190:193], v[40:43]
	v_mfma_f32_16x16x32_bf16 v[40:43], v[162:165], v[194:197], v[40:43]
	v_mfma_f32_16x16x32_bf16 v[28:31], v[144:147], v[206:209], v[28:31]
	v_mfma_f32_16x16x32_bf16 v[28:31], v[154:157], v[210:213], v[28:31]
	v_mfma_f32_16x16x32_bf16 v[24:27], v[158:161], v[206:209], v[24:27]
	v_mfma_f32_16x16x32_bf16 v[24:27], v[162:165], v[210:213], v[24:27]
	v_mfma_f32_16x16x32_bf16 v[12:15], v[144:147], v[222:225], v[12:15]
	v_mfma_f32_16x16x32_bf16 v[12:15], v[154:157], v[226:229], v[12:15]
	v_mfma_f32_16x16x32_bf16 v[8:11], v[158:161], v[222:225], v[8:11]
	v_mfma_f32_16x16x32_bf16 v[8:11], v[162:165], v[226:229], v[8:11]
	s_setprio 0
	s_setprio 1
	v_mfma_f32_16x16x32_bf16 v[52:55], v[166:169], v[182:185], v[52:55]
	v_mfma_f32_16x16x32_bf16 v[52:55], v[170:173], v[186:189], v[52:55]
	v_mfma_f32_16x16x32_bf16 v[48:51], v[174:177], v[182:185], v[48:51]
	v_mfma_f32_16x16x32_bf16 v[48:51], v[178:181], v[186:189], v[48:51]
	v_mfma_f32_16x16x32_bf16 v[36:39], v[166:169], v[190:193], v[36:39]
	v_mfma_f32_16x16x32_bf16 v[36:39], v[170:173], v[194:197], v[36:39]
	v_mfma_f32_16x16x32_bf16 v[32:35], v[174:177], v[190:193], v[32:35]
	v_mfma_f32_16x16x32_bf16 v[32:35], v[178:181], v[194:197], v[32:35]
	v_mfma_f32_16x16x32_bf16 v[20:23], v[166:169], v[206:209], v[20:23]
	v_mfma_f32_16x16x32_bf16 v[20:23], v[170:173], v[210:213], v[20:23]
	v_mfma_f32_16x16x32_bf16 v[16:19], v[174:177], v[206:209], v[16:19]
	v_mfma_f32_16x16x32_bf16 v[16:19], v[178:181], v[210:213], v[16:19]
	v_mfma_f32_16x16x32_bf16 v[4:7], v[166:169], v[222:225], v[4:7]
	v_mfma_f32_16x16x32_bf16 v[4:7], v[170:173], v[226:229], v[4:7]
	s_setprio 2
	s_barrier
	v_mfma_f32_16x16x32_bf16 v[0:3], v[174:177], v[222:225], v[0:3]
	v_mfma_f32_16x16x32_bf16 v[0:3], v[178:181], v[226:229], v[0:3]
	s_setprio 0
	s_add_u32 s26, s26, 0x100
	s_addc_u32 s27, s27, 0
	s_cmp_ge_i32 s29, s24
	s_mov_b64 s[42:43], s[40:41]
	s_mov_b32 s28, s29
	s_cbranch_scc0 .LBB0_700
	s_and_b64 vcc, exec, s[64:65]
	s_cbranch_vccz .LBB0_703
	s_barrier

; #define PG8_STAGE(bufoff, gbase, voff) do { _Pragma("unroll") for (int _i = 0; _i < 2; ++_i) \
;         __builtin_amdgcn_global_load_lds((const unsigned*)((const char*)(gbase) + (voff)[_i]), (PG8_LAS unsigned*)(lds + (bufoff) + ldsw + _i * 8192), 16, 0, 0); } while (0)
; #define PG8_LDA(dst, b, h) do { _Pragma("unroll") for (int m = 0; m < 4; ++m) _Pragma("unroll") for (int k = 0; k < 2; ++k) dst[m][k] = *(const PG8_LAS bf16x8*)(lds + PG8_SA(b, h) + aoff + m * 2048 + k * 1024); } while (0)
; #define PG8_WAIT_V(n) asm volatile("s_waitcnt vmcnt(" #n ")" ::: "memory")
; #define PG8_WAIT_L(n) asm volatile("s_waitcnt lgkmcnt(" #n ")" ::: "memory")
; #define PG8_BAR __builtin_amdgcn_s_barrier()
; template <class Epi, class Sched, bool ALIGN_EPI = true, bool SP2 = true>
; __device__ __forceinline__ void gemm_phase(PG8_LAS unsigned char* lds, const Gemm g, const Sched& S, const Epi& E, const int tid) {
;     ...
;         for (int t = 0; t < nt; t += 2) {
;             const bool last = (t == nt - 2);
;             const char* a1 = cA + (size_t)(t + 1) * kstep;
;             const char* a2 = last ? nA : cA + (size_t)(t + 2) * kstep; const char* b2 = last ? nB : cB + (size_t)(t + 2) * kstep;
;             const char* a3 = a2 + kstep; const char* b3 = b2 + kstep;
;             if (last && has_next) S.a_ready(nxt);
;             if constexpr (SP2) {
;             PG8_LDB(B0, 0, 0); PG8_LDB(B1, 0, 1); PG8_SCHED; PG8_LDA(At, 0, 0); PG8_STAGE(PG8_SA(1, 1), a1 + hstepA, voffA);
;             PG8_WAIT_V(8); PG8_WAIT_L(0); PG8_BAR; PG8_MMA(0, 0, At, B0); PG8_MMA(0, 1, At, B1); PG8_BAR; PG8_SCHED;
;             PG8_LDA(At, 0, 1); PG8_STAGE(PG8_SB(0, 0), b2, voffB); PG8_STAGE(PG8_SB(0, 1), b2 + hstepB, voffB); PG8_STAGE(PG8_SA(0, 0), a2, voffA);
;             PG8_WAIT_V(8); PG8_WAIT_L(0); PG8_BAR; PG8_MMA(1, 0, At, B0); PG8_MMA(1, 1, At, B1); PG8_BAR; PG8_SCHED;
;             PG8_LDB(B0, 1, 0); PG8_LDB(B1, 1, 1); PG8_SCHED; PG8_LDA(At, 1, 0); PG8_STAGE(PG8_SA(0, 1), a2 + hstepA, voffA);
;             PG8_WAIT_V(8); PG8_WAIT_L(0); PG8_BAR; PG8_MMA(0, 0, At, B0); PG8_MMA(0, 1, At, B1); PG8_BAR; PG8_SCHED;
;             PG8_LDA(At, 1, 1); PG8_STAGE(PG8_SB(1, 0), b3, voffB); PG8_STAGE(PG8_SB(1, 1), b3 + hstepB, voffB); PG8_STAGE(PG8_SA(1, 0), a3, voffA);
;             PG8_WAIT_V(8); PG8_WAIT_L(0); PG8_BAR; PG8_MMA(1, 0, At, B0); PG8_MMA(1, 1, At, B1); PG8_BAR; PG8_SCHED;
.LBB0_1077:
	s_add_i32 s63, s82, 2
	s_add_u32 s83, s80, 0xfff80080
	s_addc_u32 s84, s81, -1
	s_add_i32 vcc_lo, 0, 0x10000
	s_cmp_eq_u32 s29, s82
	s_cselect_b32 s85, s67, s84
	s_cselect_b32 s84, s66, s83
	v_add_u32_e32 v96, vcc_lo, v141
	s_cselect_b32 s83, s69, s61
	s_cselect_b32 s82, s68, s59
	s_add_i32 s30, 0, 0x14000
	ds_read_b128 v[146:149], v96
	ds_read_b128 v[150:153], v96 offset:1024
	ds_read_b128 v[154:157], v96 offset:2048
	ds_read_b128 v[158:161], v96 offset:3072
	v_add_u32_e32 v96, s30, v141
	ds_read_b128 v[162:165], v96
	ds_read_b128 v[166:169], v96 offset:1024
	ds_read_b128 v[170:173], v96 offset:2048
	ds_read_b128 v[174:177], v96 offset:3072
	v_lshl_add_u64 v[98:99], s[80:81], 0, v[136:137]
	s_add_i32 m0, s25, 0xc000
	ds_read_b128 v[178:181], v145
	ds_read_b128 v[182:185], v145 offset:1024
	ds_read_b128 v[186:189], v145 offset:2048
	ds_read_b128 v[190:193], v145 offset:3072
	ds_read_b128 v[194:197], v145 offset:4096
	ds_read_b128 v[200:203], v145 offset:5120
	ds_read_b128 v[206:209], v145 offset:6144
	ds_read_b128 v[210:213], v145 offset:7168
	global_load_lds_dwordx4 v[98:99], off
	v_lshl_add_u64 v[98:99], s[80:81], 0, v[138:139]
	s_add_i32 m0, s25, 0xe000
	s_nop 0
	global_load_lds_dwordx4 v[98:99], off
	s_waitcnt vmcnt(8)
	s_waitcnt lgkmcnt(0)
	s_barrier
	s_setprio 1
	s_waitcnt lgkmcnt(0)
	v_mfma_f32_16x16x32_bf16 v[92:95], v[146:149], v[178:181], v[92:95]
	v_mfma_f32_16x16x32_bf16 v[92:95], v[150:153], v[182:185], v[92:95]
	v_mfma_f32_16x16x32_bf16 v[130:133], v[154:157], v[178:181], v[130:133]
	v_mfma_f32_16x16x32_bf16 v[130:133], v[158:161], v[182:185], v[130:133]
	v_mfma_f32_16x16x32_bf16 v[126:129], v[146:149], v[186:189], v[126:129]
	v_mfma_f32_16x16x32_bf16 v[126:129], v[150:153], v[190:193], v[126:129]
	v_mfma_f32_16x16x32_bf16 v[122:125], v[154:157], v[186:189], v[122:125]
	v_mfma_f32_16x16x32_bf16 v[122:125], v[158:161], v[190:193], v[122:125]
	v_mfma_f32_16x16x32_bf16 v[118:121], v[146:149], v[194:197], v[118:121]
	v_mfma_f32_16x16x32_bf16 v[118:121], v[150:153], v[200:203], v[118:121]
	v_mfma_f32_16x16x32_bf16 v[110:113], v[154:157], v[194:197], v[110:113]
	v_mfma_f32_16x16x32_bf16 v[110:113], v[158:161], v[200:203], v[110:113]
	v_mfma_f32_16x16x32_bf16 v[76:79], v[146:149], v[206:209], v[76:79]
	v_mfma_f32_16x16x32_bf16 v[76:79], v[150:153], v[210:213], v[76:79]
	v_mfma_f32_16x16x32_bf16 v[72:75], v[154:157], v[206:209], v[72:75]
	v_mfma_f32_16x16x32_bf16 v[72:75], v[158:161], v[210:213], v[72:75]
	s_setprio 0
	s_setprio 1
	v_mfma_f32_16x16x32_bf16 v[88:91], v[162:165], v[178:181], v[88:91]
	v_mfma_f32_16x16x32_bf16 v[88:91], v[166:169], v[182:185], v[88:91]
	v_mfma_f32_16x16x32_bf16 v[84:87], v[170:173], v[178:181], v[84:87]
	v_mfma_f32_16x16x32_bf16 v[84:87], v[174:177], v[182:185], v[84:87]
	v_mfma_f32_16x16x32_bf16 v[114:117], v[162:165], v[186:189], v[114:117]
	v_mfma_f32_16x16x32_bf16 v[114:117], v[166:169], v[190:193], v[114:117]
	v_mfma_f32_16x16x32_bf16 v[106:109], v[170:173], v[186:189], v[106:109]
	v_mfma_f32_16x16x32_bf16 v[106:109], v[174:177], v[190:193], v[106:109]
	v_mfma_f32_16x16x32_bf16 v[102:105], v[162:165], v[194:197], v[102:105]
	v_mfma_f32_16x16x32_bf16 v[102:105], v[166:169], v[200:203], v[102:105]
	v_mfma_f32_16x16x32_bf16 v[80:83], v[170:173], v[194:197], v[80:83]
	v_mfma_f32_16x16x32_bf16 v[80:83], v[174:177], v[200:203], v[80:83]
	v_mfma_f32_16x16x32_bf16 v[68:71], v[162:165], v[206:209], v[68:71]
	v_mfma_f32_16x16x32_bf16 v[68:71], v[166:169], v[210:213], v[68:71]
	s_setprio 2
	s_barrier
	v_mfma_f32_16x16x32_bf16 v[64:67], v[170:173], v[206:209], v[64:67]
	v_mfma_f32_16x16x32_bf16 v[64:67], v[174:177], v[210:213], v[64:67]
	s_setprio 0
	s_add_i32 s31, vcc_lo, s24
	v_lshl_add_u64 v[98:99], s[82:83], 0, v[100:101]
	s_mov_b32 m0, s31
	ds_read_b128 v[178:181], v145 offset:16384
	ds_read_b128 v[182:185], v145 offset:17408
	ds_read_b128 v[186:189], v145 offset:18432
	ds_read_b128 v[190:193], v145 offset:19456
	ds_read_b128 v[194:197], v145 offset:20480
	ds_read_b128 v[200:203], v145 offset:21504
	ds_read_b128 v[206:209], v145 offset:22528
	ds_read_b128 v[210:213], v145 offset:23552
	global_load_lds_dwordx4 v[98:99], off
	s_add_i32 m0, s31, 0x2000
	s_add_u32 vcc_lo, s82, 0x80000
	v_lshl_add_u64 v[224:225], s[82:83], 0, v[134:135]
	s_addc_u32 vcc_hi, s83, 0
	s_add_i32 s30, s30, s24
	global_load_lds_dwordx4 v[224:225], off
	v_lshl_add_u64 v[226:227], vcc, 0, v[100:101]
	s_mov_b32 m0, s30
	v_lshl_add_u64 v[228:229], s[84:85], 0, v[134:135]
	global_load_lds_dwordx4 v[226:227], off
	v_lshl_add_u64 v[226:227], vcc, 0, v[134:135]
	s_add_i32 m0, s30, 0x2000
	s_nop 0
	global_load_lds_dwordx4 v[226:227], off
	v_lshl_add_u64 v[226:227], s[84:85], 0, v[100:101]
	s_mov_b32 m0, s25
	s_nop 0
	global_load_lds_dwordx4 v[226:227], off
	s_mov_b32 m0, s49
	s_nop 0
	global_load_lds_dwordx4 v[228:229], off
	s_waitcnt vmcnt(8)
	s_waitcnt lgkmcnt(0)
	s_barrier
; #define PG8_STAGE(bufoff, gbase, voff) do { _Pragma("unroll") for (int _i = 0; _i < 2; ++_i) \
;         __builtin_amdgcn_global_load_lds((const unsigned*)((const char*)(gbase) + (voff)[_i]), (PG8_LAS unsigned*)(lds + (bufoff) + ldsw + _i * 8192), 16, 0, 0); } while (0)
; #define PG8_LDA(dst, b, h) do { _Pragma("unroll") for (int m = 0; m < 4; ++m) _Pragma("unroll") for (int k = 0; k < 2; ++k) dst[m][k] = *(const PG8_LAS bf16x8*)(lds + PG8_SA(b, h) + aoff + m * 2048 + k * 1024); } while (0)
; #define PG8_WAIT_V(n) asm volatile("s_waitcnt vmcnt(" #n ")" ::: "memory")
; #define PG8_WAIT_L(n) asm volatile("s_waitcnt lgkmcnt(" #n ")" ::: "memory")
; #define PG8_BAR __builtin_amdgcn_s_barrier()
; template <class Epi, class Sched, bool ALIGN_EPI = true, bool SP2 = true>
; __device__ __forceinline__ void gemm_phase(PG8_LAS unsigned char* lds, const Gemm g, const Sched& S, const Epi& E, const int tid) {
;     ...
;         for (int t = 0; t < nt; t += 2) {
;             const bool last = (t == nt - 2);
;             const char* a1 = cA + (size_t)(t + 1) * kstep;
;             const char* a2 = last ? nA : cA + (size_t)(t + 2) * kstep; const char* b2 = last ? nB : cB + (size_t)(t + 2) * kstep;
;             const char* a3 = a2 + kstep; const char* b3 = b2 + kstep;
;             if (last && has_next) S.a_ready(nxt);
;             if constexpr (SP2) {
;             PG8_LDB(B0, 0, 0); PG8_LDB(B1, 0, 1); PG8_SCHED; PG8_LDA(At, 0, 0); PG8_STAGE(PG8_SA(1, 1), a1 + hstepA, voffA);
;             PG8_WAIT_V(8); PG8_WAIT_L(0); PG8_BAR; PG8_MMA(0, 0, At, B0); PG8_MMA(0, 1, At, B1); PG8_BAR; PG8_SCHED;
;             PG8_LDA(At, 0, 1); PG8_STAGE(PG8_SB(0, 0), b2, voffB); PG8_STAGE(PG8_SB(0, 1), b2 + hstepB, voffB); PG8_STAGE(PG8_SA(0, 0), a2, voffA);
;             PG8_WAIT_V(8); PG8_WAIT_L(0); PG8_BAR; PG8_MMA(1, 0, At, B0); PG8_MMA(1, 1, At, B1); PG8_BAR; PG8_SCHED;
;             PG8_LDB(B0, 1, 0); PG8_LDB(B1, 1, 1); PG8_SCHED; PG8_LDA(At, 1, 0); PG8_STAGE(PG8_SA(0, 1), a2 + hstepA, voffA);
;             PG8_WAIT_V(8); PG8_WAIT_L(0); PG8_BAR; PG8_MMA(0, 0, At, B0); PG8_MMA(0, 1, At, B1); PG8_BAR; PG8_SCHED;
;             PG8_LDA(At, 1, 1); PG8_STAGE(PG8_SB(1, 0), b3, voffB); PG8_STAGE(PG8_SB(1, 1), b3 + hstepB, voffB); PG8_STAGE(PG8_SA(1, 0), a3, voffA);
;             PG8_WAIT_V(8); PG8_WAIT_L(0); PG8_BAR; PG8_MMA(1, 0, At, B0); PG8_MMA(1, 1, At, B1); PG8_BAR; PG8_SCHED;
	s_setprio 1
	s_waitcnt lgkmcnt(0)
	v_mfma_f32_16x16x32_bf16 v[56:59], v[146:149], v[178:181], v[56:59]
	v_mfma_f32_16x16x32_bf16 v[56:59], v[150:153], v[182:185], v[56:59]
	v_mfma_f32_16x16x32_bf16 v[60:63], v[154:157], v[178:181], v[60:63]
	v_mfma_f32_16x16x32_bf16 v[60:63], v[158:161], v[182:185], v[60:63]
	v_mfma_f32_16x16x32_bf16 v[44:47], v[146:149], v[186:189], v[44:47]
	v_mfma_f32_16x16x32_bf16 v[44:47], v[150:153], v[190:193], v[44:47]
	v_mfma_f32_16x16x32_bf16 v[40:43], v[154:157], v[186:189], v[40:43]
	v_mfma_f32_16x16x32_bf16 v[40:43], v[158:161], v[190:193], v[40:43]
	v_mfma_f32_16x16x32_bf16 v[28:31], v[146:149], v[194:197], v[28:31]
	v_mfma_f32_16x16x32_bf16 v[28:31], v[150:153], v[200:203], v[28:31]
	v_mfma_f32_16x16x32_bf16 v[24:27], v[154:157], v[194:197], v[24:27]
	v_mfma_f32_16x16x32_bf16 v[24:27], v[158:161], v[200:203], v[24:27]
	v_mfma_f32_16x16x32_bf16 v[12:15], v[146:149], v[206:209], v[12:15]
	v_mfma_f32_16x16x32_bf16 v[12:15], v[150:153], v[210:213], v[12:15]
	v_mfma_f32_16x16x32_bf16 v[8:11], v[154:157], v[206:209], v[8:11]
	v_mfma_f32_16x16x32_bf16 v[8:11], v[158:161], v[210:213], v[8:11]
	s_setprio 0
	s_setprio 1
	v_mfma_f32_16x16x32_bf16 v[52:55], v[162:165], v[178:181], v[52:55]
	v_mfma_f32_16x16x32_bf16 v[52:55], v[166:169], v[182:185], v[52:55]
	v_mfma_f32_16x16x32_bf16 v[48:51], v[170:173], v[178:181], v[48:51]
	v_mfma_f32_16x16x32_bf16 v[48:51], v[174:177], v[182:185], v[48:51]
	v_mfma_f32_16x16x32_bf16 v[36:39], v[162:165], v[186:189], v[36:39]
	v_mfma_f32_16x16x32_bf16 v[36:39], v[166:169], v[190:193], v[36:39]
	v_mfma_f32_16x16x32_bf16 v[32:35], v[170:173], v[186:189], v[32:35]
	v_mfma_f32_16x16x32_bf16 v[32:35], v[174:177], v[190:193], v[32:35]
	v_mfma_f32_16x16x32_bf16 v[20:23], v[162:165], v[194:197], v[20:23]
	v_mfma_f32_16x16x32_bf16 v[20:23], v[166:169], v[200:203], v[20:23]
	v_mfma_f32_16x16x32_bf16 v[16:19], v[170:173], v[194:197], v[16:19]
	v_mfma_f32_16x16x32_bf16 v[16:19], v[174:177], v[200:203], v[16:19]
	v_mfma_f32_16x16x32_bf16 v[4:7], v[162:165], v[206:209], v[4:7]
	v_mfma_f32_16x16x32_bf16 v[4:7], v[166:169], v[210:213], v[4:7]
	s_setprio 2
	s_barrier
	v_mfma_f32_16x16x32_bf16 v[0:3], v[170:173], v[206:209], v[0:3]
	v_mfma_f32_16x16x32_bf16 v[0:3], v[174:177], v[210:213], v[0:3]
	s_setprio 0
	s_add_i32 s30, 0, 0x18000
	v_add_u32_e32 v96, s30, v141
	s_add_i32 s31, 0, 0x1c000
	ds_read_b128 v[146:149], v96
	ds_read_b128 v[150:153], v96 offset:1024
	ds_read_b128 v[154:157], v96 offset:2048
	ds_read_b128 v[158:161], v96 offset:3072
	v_add_u32_e32 v96, s31, v141
	ds_read_b128 v[162:165], v96
	ds_read_b128 v[166:169], v96 offset:1024
	ds_read_b128 v[170:173], v96 offset:2048
	ds_read_b128 v[174:177], v96 offset:3072
	s_add_u32 s84, s84, 0x80000
	s_addc_u32 s85, s85, 0
	s_mov_b32 m0, s51
	v_lshl_add_u64 v[230:231], s[84:85], 0, v[100:101]
	ds_read_b128 v[178:181], v145 offset:32768
	ds_read_b128 v[182:185], v145 offset:33792
	ds_read_b128 v[186:189], v145 offset:34816
	ds_read_b128 v[190:193], v145 offset:35840
	ds_read_b128 v[194:197], v145 offset:36864
	ds_read_b128 v[200:203], v145 offset:37888
	ds_read_b128 v[206:209], v145 offset:38912
	ds_read_b128 v[210:213], v145 offset:39936
	global_load_lds_dwordx4 v[230:231], off
	v_lshl_add_u64 v[230:231], s[84:85], 0, v[134:135]
	s_mov_b32 m0, s76
	s_nop 0
	global_load_lds_dwordx4 v[230:231], off
	s_waitcnt vmcnt(8)
	s_waitcnt lgkmcnt(0)
	s_barrier
	s_setprio 1
	s_waitcnt lgkmcnt(0)
	v_mfma_f32_16x16x32_bf16 v[92:95], v[146:149], v[178:181], v[92:95]
	v_mfma_f32_16x16x32_bf16 v[92:95], v[150:153], v[182:185], v[92:95]
	v_mfma_f32_16x16x32_bf16 v[130:133], v[154:157], v[178:181], v[130:133]
	v_mfma_f32_16x16x32_bf16 v[130:133], v[158:161], v[182:185], v[130:133]
	v_mfma_f32_16x16x32_bf16 v[126:129], v[146:149], v[186:189], v[126:129]
	v_mfma_f32_16x16x32_bf16 v[126:129], v[150:153], v[190:193], v[126:129]
	v_mfma_f32_16x16x32_bf16 v[122:125], v[154:157], v[186:189], v[122:125]
	v_mfma_f32_16x16x32_bf16 v[122:125], v[158:161], v[190:193], v[122:125]
	v_mfma_f32_16x16x32_bf16 v[118:121], v[146:149], v[194:197], v[118:121]
	v_mfma_f32_16x16x32_bf16 v[118:121], v[150:153], v[200:203], v[118:121]
	v_mfma_f32_16x16x32_bf16 v[110:113], v[154:157], v[194:197], v[110:113]
	v_mfma_f32_16x16x32_bf16 v[110:113], v[158:161], v[200:203], v[110:113]
	v_mfma_f32_16x16x32_bf16 v[76:79], v[146:149], v[206:209], v[76:79]
	v_mfma_f32_16x16x32_bf16 v[76:79], v[150:153], v[210:213], v[76:79]
	v_mfma_f32_16x16x32_bf16 v[72:75], v[154:157], v[206:209], v[72:75]
	v_mfma_f32_16x16x32_bf16 v[72:75], v[158:161], v[210:213], v[72:75]
	s_setprio 0
	s_setprio 1
	v_mfma_f32_16x16x32_bf16 v[88:91], v[162:165], v[178:181], v[88:91]
	v_mfma_f32_16x16x32_bf16 v[88:91], v[166:169], v[182:185], v[88:91]
	v_mfma_f32_16x16x32_bf16 v[84:87], v[170:173], v[178:181], v[84:87]
	v_mfma_f32_16x16x32_bf16 v[84:87], v[174:177], v[182:185], v[84:87]
	v_mfma_f32_16x16x32_bf16 v[114:117], v[162:165], v[186:189], v[114:117]
	v_mfma_f32_16x16x32_bf16 v[114:117], v[166:169], v[190:193], v[114:117]
	v_mfma_f32_16x16x32_bf16 v[106:109], v[170:173], v[186:189], v[106:109]
	v_mfma_f32_16x16x32_bf16 v[106:109], v[174:177], v[190:193], v[106:109]
	v_mfma_f32_16x16x32_bf16 v[102:105], v[162:165], v[194:197], v[102:105]
	v_mfma_f32_16x16x32_bf16 v[102:105], v[166:169], v[200:203], v[102:105]
	v_mfma_f32_16x16x32_bf16 v[80:83], v[170:173], v[194:197], v[80:83]
	v_mfma_f32_16x16x32_bf16 v[80:83], v[174:177], v[200:203], v[80:83]
	v_mfma_f32_16x16x32_bf16 v[68:71], v[162:165], v[206:209], v[68:71]
	v_mfma_f32_16x16x32_bf16 v[68:71], v[166:169], v[210:213], v[68:71]
	s_setprio 2
	s_barrier
; #define PG8_STAGE(bufoff, gbase, voff) do { _Pragma("unroll") for (int _i = 0; _i < 2; ++_i) \
;         __builtin_amdgcn_global_load_lds((const unsigned*)((const char*)(gbase) + (voff)[_i]), (PG8_LAS unsigned*)(lds + (bufoff) + ldsw + _i * 8192), 16, 0, 0); } while (0)
; #define PG8_LDA(dst, b, h) do { _Pragma("unroll") for (int m = 0; m < 4; ++m) _Pragma("unroll") for (int k = 0; k < 2; ++k) dst[m][k] = *(const PG8_LAS bf16x8*)(lds + PG8_SA(b, h) + aoff + m * 2048 + k * 1024); } while (0)
; #define PG8_WAIT_V(n) asm volatile("s_waitcnt vmcnt(" #n ")" ::: "memory")
; #define PG8_WAIT_L(n) asm volatile("s_waitcnt lgkmcnt(" #n ")" ::: "memory")
; #define PG8_BAR __builtin_amdgcn_s_barrier()
; template <class Epi, class Sched, bool ALIGN_EPI = true, bool SP2 = true>
; __device__ __forceinline__ void gemm_phase(PG8_LAS unsigned char* lds, const Gemm g, const Sched& S, const Epi& E, const int tid) {
;     ...
;         for (int t = 0; t < nt; t += 2) {
;             const bool last = (t == nt - 2);
;             const char* a1 = cA + (size_t)(t + 1) * kstep;
;             const char* a2 = last ? nA : cA + (size_t)(t + 2) * kstep; const char* b2 = last ? nB : cB + (size_t)(t + 2) * kstep;
;             const char* a3 = a2 + kstep; const char* b3 = b2 + kstep;
;             if (last && has_next) S.a_ready(nxt);
;             if constexpr (SP2) {
;             PG8_LDB(B0, 0, 0); PG8_LDB(B1, 0, 1); PG8_SCHED; PG8_LDA(At, 0, 0); PG8_STAGE(PG8_SA(1, 1), a1 + hstepA, voffA);
;             PG8_WAIT_V(8); PG8_WAIT_L(0); PG8_BAR; PG8_MMA(0, 0, At, B0); PG8_MMA(0, 1, At, B1); PG8_BAR; PG8_SCHED;
;             PG8_LDA(At, 0, 1); PG8_STAGE(PG8_SB(0, 0), b2, voffB); PG8_STAGE(PG8_SB(0, 1), b2 + hstepB, voffB); PG8_STAGE(PG8_SA(0, 0), a2, voffA);
;             PG8_WAIT_V(8); PG8_WAIT_L(0); PG8_BAR; PG8_MMA(1, 0, At, B0); PG8_MMA(1, 1, At, B1); PG8_BAR; PG8_SCHED;
;             PG8_LDB(B0, 1, 0); PG8_LDB(B1, 1, 1); PG8_SCHED; PG8_LDA(At, 1, 0); PG8_STAGE(PG8_SA(0, 1), a2 + hstepA, voffA);
;             PG8_WAIT_V(8); PG8_WAIT_L(0); PG8_BAR; PG8_MMA(0, 0, At, B0); PG8_MMA(0, 1, At, B1); PG8_BAR; PG8_SCHED;
;             PG8_LDA(At, 1, 1); PG8_STAGE(PG8_SB(1, 0), b3, voffB); PG8_STAGE(PG8_SB(1, 1), b3 + hstepB, voffB); PG8_STAGE(PG8_SA(1, 0), a3, voffA);
;             PG8_WAIT_V(8); PG8_WAIT_L(0); PG8_BAR; PG8_MMA(1, 0, At, B0); PG8_MMA(1, 1, At, B1); PG8_BAR; PG8_SCHED;
	v_mfma_f32_16x16x32_bf16 v[64:67], v[170:173], v[206:209], v[64:67]
	v_mfma_f32_16x16x32_bf16 v[64:67], v[174:177], v[210:213], v[64:67]
	s_setprio 0
	s_add_i32 s30, s30, s24
	v_lshl_add_u64 v[98:99], v[98:99], 0, s[4:5]
	s_mov_b32 m0, s30
	ds_read_b128 v[178:181], v145 offset:49152
	ds_read_b128 v[182:185], v145 offset:50176
	ds_read_b128 v[186:189], v145 offset:51200
	ds_read_b128 v[190:193], v145 offset:52224
	ds_read_b128 v[194:197], v145 offset:53248
	ds_read_b128 v[200:203], v145 offset:54272
	ds_read_b128 v[206:209], v145 offset:55296
	ds_read_b128 v[210:213], v145 offset:56320
	global_load_lds_dwordx4 v[98:99], off
	s_add_i32 m0, s30, 0x2000
	s_add_u32 s82, s82, 0x80080
	v_lshl_add_u64 v[98:99], v[224:225], 0, s[4:5]
	s_addc_u32 s83, s83, 0
	s_add_i32 s30, s31, s24
	global_load_lds_dwordx4 v[98:99], off
	v_lshl_add_u64 v[98:99], s[82:83], 0, v[100:101]
	s_mov_b32 m0, s30
	s_nop 0
	global_load_lds_dwordx4 v[98:99], off
	v_lshl_add_u64 v[98:99], s[82:83], 0, v[134:135]
	s_add_i32 m0, s30, 0x2000
	s_nop 0
	global_load_lds_dwordx4 v[98:99], off
	v_lshl_add_u64 v[98:99], v[226:227], 0, s[4:5]
	s_mov_b32 m0, s90
	s_nop 0
	global_load_lds_dwordx4 v[98:99], off
	v_lshl_add_u64 v[98:99], v[228:229], 0, s[4:5]
	s_mov_b32 m0, s91
	s_nop 0
	global_load_lds_dwordx4 v[98:99], off
	s_waitcnt vmcnt(8)
	s_waitcnt lgkmcnt(0)
	s_barrier
	s_setprio 1
	s_waitcnt lgkmcnt(0)
	v_mfma_f32_16x16x32_bf16 v[56:59], v[146:149], v[178:181], v[56:59]
	v_mfma_f32_16x16x32_bf16 v[56:59], v[150:153], v[182:185], v[56:59]
	v_mfma_f32_16x16x32_bf16 v[60:63], v[154:157], v[178:181], v[60:63]
	v_mfma_f32_16x16x32_bf16 v[60:63], v[158:161], v[182:185], v[60:63]
	v_mfma_f32_16x16x32_bf16 v[44:47], v[146:149], v[186:189], v[44:47]
	v_mfma_f32_16x16x32_bf16 v[44:47], v[150:153], v[190:193], v[44:47]
	v_mfma_f32_16x16x32_bf16 v[40:43], v[154:157], v[186:189], v[40:43]
	v_mfma_f32_16x16x32_bf16 v[40:43], v[158:161], v[190:193], v[40:43]
	v_mfma_f32_16x16x32_bf16 v[28:31], v[146:149], v[194:197], v[28:31]
	v_mfma_f32_16x16x32_bf16 v[28:31], v[150:153], v[200:203], v[28:31]
	v_mfma_f32_16x16x32_bf16 v[24:27], v[154:157], v[194:197], v[24:27]
	v_mfma_f32_16x16x32_bf16 v[24:27], v[158:161], v[200:203], v[24:27]
	v_mfma_f32_16x16x32_bf16 v[12:15], v[146:149], v[206:209], v[12:15]
	v_mfma_f32_16x16x32_bf16 v[12:15], v[150:153], v[210:213], v[12:15]
	v_mfma_f32_16x16x32_bf16 v[8:11], v[154:157], v[206:209], v[8:11]
	v_mfma_f32_16x16x32_bf16 v[8:11], v[158:161], v[210:213], v[8:11]
	s_setprio 0
	s_setprio 1
	v_mfma_f32_16x16x32_bf16 v[52:55], v[162:165], v[178:181], v[52:55]
	v_mfma_f32_16x16x32_bf16 v[52:55], v[166:169], v[182:185], v[52:55]
	v_mfma_f32_16x16x32_bf16 v[48:51], v[170:173], v[178:181], v[48:51]
	v_mfma_f32_16x16x32_bf16 v[48:51], v[174:177], v[182:185], v[48:51]
	v_mfma_f32_16x16x32_bf16 v[36:39], v[162:165], v[186:189], v[36:39]
	v_mfma_f32_16x16x32_bf16 v[36:39], v[166:169], v[190:193], v[36:39]
	v_mfma_f32_16x16x32_bf16 v[32:35], v[170:173], v[186:189], v[32:35]
	v_mfma_f32_16x16x32_bf16 v[32:35], v[174:177], v[190:193], v[32:35]
	v_mfma_f32_16x16x32_bf16 v[20:23], v[162:165], v[194:197], v[20:23]
	v_mfma_f32_16x16x32_bf16 v[20:23], v[166:169], v[200:203], v[20:23]
	v_mfma_f32_16x16x32_bf16 v[16:19], v[170:173], v[194:197], v[16:19]
	v_mfma_f32_16x16x32_bf16 v[16:19], v[174:177], v[200:203], v[16:19]
	v_mfma_f32_16x16x32_bf16 v[4:7], v[162:165], v[206:209], v[4:7]
	v_mfma_f32_16x16x32_bf16 v[4:7], v[166:169], v[210:213], v[4:7]
	s_setprio 2
	s_barrier
	v_mfma_f32_16x16x32_bf16 v[0:3], v[170:173], v[206:209], v[0:3]
	v_mfma_f32_16x16x32_bf16 v[0:3], v[174:177], v[210:213], v[0:3]
	s_setprio 0
	s_add_u32 s80, s80, 0x100
	s_addc_u32 s81, s81, 0
	s_add_u32 s59, s59, 0x100
	s_addc_u32 s61, s61, 0
	s_cmp_ge_i32 s63, s57
	s_mov_b32 s82, s63
	s_cbranch_scc0 .LBB0_1077

; #define PG8_STAGE(bufoff, gbase, voff) do { _Pragma("unroll") for (int _i = 0; _i < 2; ++_i) \
;         __builtin_amdgcn_global_load_lds((const unsigned*)((const char*)(gbase) + (voff)[_i]), (PG8_LAS unsigned*)(lds + (bufoff) + ldsw + _i * 8192), 16, 0, 0); } while (0)
; #define PG8_LDA(dst, b, h) do { _Pragma("unroll") for (int m = 0; m < 4; ++m) _Pragma("unroll") for (int k = 0; k < 2; ++k) dst[m][k] = *(const PG8_LAS bf16x8*)(lds + PG8_SA(b, h) + aoff + m * 2048 + k * 1024); } while (0)
; #define PG8_WAIT_V(n) asm volatile("s_waitcnt vmcnt(" #n ")" ::: "memory")
; #define PG8_WAIT_L(n) asm volatile("s_waitcnt lgkmcnt(" #n ")" ::: "memory")
; #define PG8_BAR __builtin_amdgcn_s_barrier()
; template <class Epi, class Sched, bool ALIGN_EPI = true, bool SP2 = true>
; __device__ __forceinline__ void gemm_phase(PG8_LAS unsigned char* lds, const Gemm g, const Sched& S, const Epi& E, const int tid) {
;     ...
;         for (int t = 0; t < nt; t += 2) {
;             const bool last = (t == nt - 2);
;             const char* a1 = cA + (size_t)(t + 1) * kstep;
;             const char* a2 = last ? nA : cA + (size_t)(t + 2) * kstep; const char* b2 = last ? nB : cB + (size_t)(t + 2) * kstep;
;             const char* a3 = a2 + kstep; const char* b3 = b2 + kstep;
;             if (last && has_next) S.a_ready(nxt);
;             if constexpr (SP2) {
;             PG8_LDB(B0, 0, 0); PG8_LDB(B1, 0, 1); PG8_SCHED; PG8_LDA(At, 0, 0); PG8_STAGE(PG8_SA(1, 1), a1 + hstepA, voffA);
;             PG8_WAIT_V(8); PG8_WAIT_L(0); PG8_BAR; PG8_MMA(0, 0, At, B0); PG8_MMA(0, 1, At, B1); PG8_BAR; PG8_SCHED;
;             PG8_LDA(At, 0, 1); PG8_STAGE(PG8_SB(0, 0), b2, voffB); PG8_STAGE(PG8_SB(0, 1), b2 + hstepB, voffB); PG8_STAGE(PG8_SA(0, 0), a2, voffA);
;             PG8_WAIT_V(8); PG8_WAIT_L(0); PG8_BAR; PG8_MMA(1, 0, At, B0); PG8_MMA(1, 1, At, B1); PG8_BAR; PG8_SCHED;
;             PG8_LDB(B0, 1, 0); PG8_LDB(B1, 1, 1); PG8_SCHED; PG8_LDA(At, 1, 0); PG8_STAGE(PG8_SA(0, 1), a2 + hstepA, voffA);
;             PG8_WAIT_V(8); PG8_WAIT_L(0); PG8_BAR; PG8_MMA(0, 0, At, B0); PG8_MMA(0, 1, At, B1); PG8_BAR; PG8_SCHED;
;             PG8_LDA(At, 1, 1); PG8_STAGE(PG8_SB(1, 0), b3, voffB); PG8_STAGE(PG8_SB(1, 1), b3 + hstepB, voffB); PG8_STAGE(PG8_SA(1, 0), a3, voffA);
;             PG8_WAIT_V(8); PG8_WAIT_L(0); PG8_BAR; PG8_MMA(1, 0, At, B0); PG8_MMA(1, 1, At, B1); PG8_BAR; PG8_SCHED;
.LBB0_1319:
	s_add_u32 s28, s62, 0xfff80080
	s_addc_u32 s29, s63, -1
	s_add_i32 s30, 0, 0x10000
	s_cmp_eq_u32 s52, 28
	s_cselect_b32 s67, s24, s29
	s_cselect_b32 s66, s25, s28
	v_add_u32_e32 v145, s30, v142
	s_cselect_b32 s65, s26, s51
	s_cselect_b32 s64, s27, s49
	s_add_i32 s31, 0, 0x14000
	ds_read_b128 v[146:149], v145
	ds_read_b128 v[150:153], v145 offset:1024
	ds_read_b128 v[154:157], v145 offset:2048
	ds_read_b128 v[158:161], v145 offset:3072
	v_add_u32_e32 v145, s31, v142
	ds_read_b128 v[162:165], v145
	ds_read_b128 v[166:169], v145 offset:1024
	ds_read_b128 v[170:173], v145 offset:2048
	ds_read_b128 v[174:177], v145 offset:3072
	v_lshl_add_u64 v[222:223], s[62:63], 0, v[138:139]
	s_add_i32 m0, s22, 0xc000
	ds_read_b128 v[178:181], v144
	ds_read_b128 v[182:185], v144 offset:1024
	ds_read_b128 v[186:189], v144 offset:2048
	ds_read_b128 v[190:193], v144 offset:3072
	ds_read_b128 v[194:197], v144 offset:4096
	ds_read_b128 v[200:203], v144 offset:5120
	ds_read_b128 v[206:209], v144 offset:6144
	ds_read_b128 v[210:213], v144 offset:7168
	global_load_lds_dwordx4 v[222:223], off
	v_lshl_add_u64 v[222:223], s[62:63], 0, v[140:141]
	s_add_i32 m0, s22, 0xe000
	s_nop 0
	global_load_lds_dwordx4 v[222:223], off
	s_waitcnt vmcnt(8)
	s_waitcnt lgkmcnt(0)
	s_barrier
	s_setprio 1
	s_waitcnt lgkmcnt(0)
	v_mfma_f32_16x16x32_bf16 v[126:129], v[146:149], v[178:181], v[126:129]
	v_mfma_f32_16x16x32_bf16 v[126:129], v[150:153], v[182:185], v[126:129]
	v_mfma_f32_16x16x32_bf16 v[118:121], v[154:157], v[178:181], v[118:121]
	v_mfma_f32_16x16x32_bf16 v[118:121], v[158:161], v[182:185], v[118:121]
	v_mfma_f32_16x16x32_bf16 v[110:113], v[146:149], v[186:189], v[110:113]
	v_mfma_f32_16x16x32_bf16 v[110:113], v[150:153], v[190:193], v[110:113]
	v_mfma_f32_16x16x32_bf16 v[102:105], v[154:157], v[186:189], v[102:105]
	v_mfma_f32_16x16x32_bf16 v[102:105], v[158:161], v[190:193], v[102:105]
	v_mfma_f32_16x16x32_bf16 v[92:95], v[146:149], v[194:197], v[92:95]
	v_mfma_f32_16x16x32_bf16 v[92:95], v[150:153], v[200:203], v[92:95]
	v_mfma_f32_16x16x32_bf16 v[84:87], v[154:157], v[194:197], v[84:87]
	v_mfma_f32_16x16x32_bf16 v[84:87], v[158:161], v[200:203], v[84:87]
	v_mfma_f32_16x16x32_bf16 v[76:79], v[146:149], v[206:209], v[76:79]
	v_mfma_f32_16x16x32_bf16 v[76:79], v[150:153], v[210:213], v[76:79]
	v_mfma_f32_16x16x32_bf16 v[68:71], v[154:157], v[206:209], v[68:71]
	v_mfma_f32_16x16x32_bf16 v[68:71], v[158:161], v[210:213], v[68:71]
	s_setprio 0
	s_setprio 1
	v_mfma_f32_16x16x32_bf16 v[122:125], v[162:165], v[178:181], v[122:125]
	v_mfma_f32_16x16x32_bf16 v[122:125], v[166:169], v[182:185], v[122:125]
	v_mfma_f32_16x16x32_bf16 v[114:117], v[170:173], v[178:181], v[114:117]
	v_mfma_f32_16x16x32_bf16 v[114:117], v[174:177], v[182:185], v[114:117]
	v_mfma_f32_16x16x32_bf16 v[106:109], v[162:165], v[186:189], v[106:109]
	v_mfma_f32_16x16x32_bf16 v[106:109], v[166:169], v[190:193], v[106:109]
	v_mfma_f32_16x16x32_bf16 v[98:101], v[170:173], v[186:189], v[98:101]
	v_mfma_f32_16x16x32_bf16 v[98:101], v[174:177], v[190:193], v[98:101]
	v_mfma_f32_16x16x32_bf16 v[88:91], v[162:165], v[194:197], v[88:91]
	v_mfma_f32_16x16x32_bf16 v[88:91], v[166:169], v[200:203], v[88:91]
	v_mfma_f32_16x16x32_bf16 v[80:83], v[170:173], v[194:197], v[80:83]
	v_mfma_f32_16x16x32_bf16 v[80:83], v[174:177], v[200:203], v[80:83]
	v_mfma_f32_16x16x32_bf16 v[72:75], v[162:165], v[206:209], v[72:75]
	v_mfma_f32_16x16x32_bf16 v[72:75], v[166:169], v[210:213], v[72:75]
	s_setprio 2
	s_barrier
	v_mfma_f32_16x16x32_bf16 v[64:67], v[170:173], v[206:209], v[64:67]
	v_mfma_f32_16x16x32_bf16 v[64:67], v[174:177], v[210:213], v[64:67]
	s_setprio 0
	s_add_i32 s28, s30, s21
	v_lshl_add_u64 v[222:223], s[64:65], 0, v[134:135]
	s_mov_b32 m0, s28
	ds_read_b128 v[178:181], v144 offset:16384
	ds_read_b128 v[182:185], v144 offset:17408
	ds_read_b128 v[186:189], v144 offset:18432
	ds_read_b128 v[190:193], v144 offset:19456
	ds_read_b128 v[194:197], v144 offset:20480
	ds_read_b128 v[200:203], v144 offset:21504
	ds_read_b128 v[206:209], v144 offset:22528
	ds_read_b128 v[210:213], v144 offset:23552
	global_load_lds_dwordx4 v[222:223], off
	s_add_i32 m0, s28, 0x2000
	s_add_u32 s28, s64, 0x80000
	v_lshl_add_u64 v[224:225], s[64:65], 0, v[130:131]
	s_addc_u32 s29, s65, 0
	s_add_i32 s30, s31, s21
	global_load_lds_dwordx4 v[224:225], off
	v_lshl_add_u64 v[226:227], s[28:29], 0, v[134:135]
	s_mov_b32 m0, s30
	v_lshl_add_u64 v[228:229], s[66:67], 0, v[132:133]
	global_load_lds_dwordx4 v[226:227], off
	v_lshl_add_u64 v[226:227], s[28:29], 0, v[130:131]
	s_add_i32 m0, s30, 0x2000
	s_nop 0
	global_load_lds_dwordx4 v[226:227], off
	v_lshl_add_u64 v[226:227], s[66:67], 0, v[136:137]
	s_mov_b32 m0, s22
	s_nop 0
	global_load_lds_dwordx4 v[226:227], off
	s_mov_b32 m0, s23
	s_nop 0
	global_load_lds_dwordx4 v[228:229], off
	s_waitcnt vmcnt(8)
	s_waitcnt lgkmcnt(0)
	s_barrier
; #define PG8_STAGE(bufoff, gbase, voff) do { _Pragma("unroll") for (int _i = 0; _i < 2; ++_i) \
;         __builtin_amdgcn_global_load_lds((const unsigned*)((const char*)(gbase) + (voff)[_i]), (PG8_LAS unsigned*)(lds + (bufoff) + ldsw + _i * 8192), 16, 0, 0); } while (0)
; #define PG8_LDA(dst, b, h) do { _Pragma("unroll") for (int m = 0; m < 4; ++m) _Pragma("unroll") for (int k = 0; k < 2; ++k) dst[m][k] = *(const PG8_LAS bf16x8*)(lds + PG8_SA(b, h) + aoff + m * 2048 + k * 1024); } while (0)
; #define PG8_WAIT_V(n) asm volatile("s_waitcnt vmcnt(" #n ")" ::: "memory")
; #define PG8_WAIT_L(n) asm volatile("s_waitcnt lgkmcnt(" #n ")" ::: "memory")
; #define PG8_BAR __builtin_amdgcn_s_barrier()
; template <class Epi, class Sched, bool ALIGN_EPI = true, bool SP2 = true>
; __device__ __forceinline__ void gemm_phase(PG8_LAS unsigned char* lds, const Gemm g, const Sched& S, const Epi& E, const int tid) {
;     ...
;         for (int t = 0; t < nt; t += 2) {
;             const bool last = (t == nt - 2);
;             const char* a1 = cA + (size_t)(t + 1) * kstep;
;             const char* a2 = last ? nA : cA + (size_t)(t + 2) * kstep; const char* b2 = last ? nB : cB + (size_t)(t + 2) * kstep;
;             const char* a3 = a2 + kstep; const char* b3 = b2 + kstep;
;             if (last && has_next) S.a_ready(nxt);
;             if constexpr (SP2) {
;             PG8_LDB(B0, 0, 0); PG8_LDB(B1, 0, 1); PG8_SCHED; PG8_LDA(At, 0, 0); PG8_STAGE(PG8_SA(1, 1), a1 + hstepA, voffA);
;             PG8_WAIT_V(8); PG8_WAIT_L(0); PG8_BAR; PG8_MMA(0, 0, At, B0); PG8_MMA(0, 1, At, B1); PG8_BAR; PG8_SCHED;
;             PG8_LDA(At, 0, 1); PG8_STAGE(PG8_SB(0, 0), b2, voffB); PG8_STAGE(PG8_SB(0, 1), b2 + hstepB, voffB); PG8_STAGE(PG8_SA(0, 0), a2, voffA);
;             PG8_WAIT_V(8); PG8_WAIT_L(0); PG8_BAR; PG8_MMA(1, 0, At, B0); PG8_MMA(1, 1, At, B1); PG8_BAR; PG8_SCHED;
;             PG8_LDB(B0, 1, 0); PG8_LDB(B1, 1, 1); PG8_SCHED; PG8_LDA(At, 1, 0); PG8_STAGE(PG8_SA(0, 1), a2 + hstepA, voffA);
;             PG8_WAIT_V(8); PG8_WAIT_L(0); PG8_BAR; PG8_MMA(0, 0, At, B0); PG8_MMA(0, 1, At, B1); PG8_BAR; PG8_SCHED;
;             PG8_LDA(At, 1, 1); PG8_STAGE(PG8_SB(1, 0), b3, voffB); PG8_STAGE(PG8_SB(1, 1), b3 + hstepB, voffB); PG8_STAGE(PG8_SA(1, 0), a3, voffA);
;             PG8_WAIT_V(8); PG8_WAIT_L(0); PG8_BAR; PG8_MMA(1, 0, At, B0); PG8_MMA(1, 1, At, B1); PG8_BAR; PG8_SCHED;
	s_setprio 1
	s_waitcnt lgkmcnt(0)
	v_mfma_f32_16x16x32_bf16 v[60:63], v[146:149], v[178:181], v[60:63]
	v_mfma_f32_16x16x32_bf16 v[60:63], v[150:153], v[182:185], v[60:63]
	v_mfma_f32_16x16x32_bf16 v[52:55], v[154:157], v[178:181], v[52:55]
	v_mfma_f32_16x16x32_bf16 v[52:55], v[158:161], v[182:185], v[52:55]
	v_mfma_f32_16x16x32_bf16 v[44:47], v[146:149], v[186:189], v[44:47]
	v_mfma_f32_16x16x32_bf16 v[44:47], v[150:153], v[190:193], v[44:47]
	v_mfma_f32_16x16x32_bf16 v[36:39], v[154:157], v[186:189], v[36:39]
	v_mfma_f32_16x16x32_bf16 v[36:39], v[158:161], v[190:193], v[36:39]
	v_mfma_f32_16x16x32_bf16 v[28:31], v[146:149], v[194:197], v[28:31]
	v_mfma_f32_16x16x32_bf16 v[28:31], v[150:153], v[200:203], v[28:31]
	v_mfma_f32_16x16x32_bf16 v[20:23], v[154:157], v[194:197], v[20:23]
	v_mfma_f32_16x16x32_bf16 v[20:23], v[158:161], v[200:203], v[20:23]
	v_mfma_f32_16x16x32_bf16 v[12:15], v[146:149], v[206:209], v[12:15]
	v_mfma_f32_16x16x32_bf16 v[12:15], v[150:153], v[210:213], v[12:15]
	v_mfma_f32_16x16x32_bf16 v[4:7], v[154:157], v[206:209], v[4:7]
	v_mfma_f32_16x16x32_bf16 v[4:7], v[158:161], v[210:213], v[4:7]
	s_setprio 0
	s_setprio 1
	v_mfma_f32_16x16x32_bf16 v[56:59], v[162:165], v[178:181], v[56:59]
	v_mfma_f32_16x16x32_bf16 v[56:59], v[166:169], v[182:185], v[56:59]
	v_mfma_f32_16x16x32_bf16 v[48:51], v[170:173], v[178:181], v[48:51]
	v_mfma_f32_16x16x32_bf16 v[48:51], v[174:177], v[182:185], v[48:51]
	v_mfma_f32_16x16x32_bf16 v[40:43], v[162:165], v[186:189], v[40:43]
	v_mfma_f32_16x16x32_bf16 v[40:43], v[166:169], v[190:193], v[40:43]
	v_mfma_f32_16x16x32_bf16 v[32:35], v[170:173], v[186:189], v[32:35]
	v_mfma_f32_16x16x32_bf16 v[32:35], v[174:177], v[190:193], v[32:35]
	v_mfma_f32_16x16x32_bf16 v[24:27], v[162:165], v[194:197], v[24:27]
	v_mfma_f32_16x16x32_bf16 v[24:27], v[166:169], v[200:203], v[24:27]
	v_mfma_f32_16x16x32_bf16 v[16:19], v[170:173], v[194:197], v[16:19]
	v_mfma_f32_16x16x32_bf16 v[16:19], v[174:177], v[200:203], v[16:19]
	v_mfma_f32_16x16x32_bf16 v[8:11], v[162:165], v[206:209], v[8:11]
	v_mfma_f32_16x16x32_bf16 v[8:11], v[166:169], v[210:213], v[8:11]
	s_setprio 2
	s_barrier
	v_mfma_f32_16x16x32_bf16 v[0:3], v[170:173], v[206:209], v[0:3]
	v_mfma_f32_16x16x32_bf16 v[0:3], v[174:177], v[210:213], v[0:3]
	s_setprio 0
	s_add_i32 s30, 0, 0x18000
	v_add_u32_e32 v145, s30, v142
	s_add_i32 s31, 0, 0x1c000
	ds_read_b128 v[146:149], v145
	ds_read_b128 v[150:153], v145 offset:1024
	ds_read_b128 v[154:157], v145 offset:2048
	ds_read_b128 v[158:161], v145 offset:3072
	v_add_u32_e32 v145, s31, v142
	ds_read_b128 v[162:165], v145
	ds_read_b128 v[166:169], v145 offset:1024
	ds_read_b128 v[170:173], v145 offset:2048
	ds_read_b128 v[174:177], v145 offset:3072
	s_add_u32 s28, s66, 0x80000
	s_addc_u32 s29, s67, 0
	s_mov_b32 m0, s61
	v_lshl_add_u64 v[230:231], s[28:29], 0, v[136:137]
	ds_read_b128 v[178:181], v144 offset:32768
	ds_read_b128 v[182:185], v144 offset:33792
	ds_read_b128 v[186:189], v144 offset:34816
	ds_read_b128 v[190:193], v144 offset:35840
	ds_read_b128 v[194:197], v144 offset:36864
	ds_read_b128 v[200:203], v144 offset:37888
	ds_read_b128 v[206:209], v144 offset:38912
	ds_read_b128 v[210:213], v144 offset:39936
	global_load_lds_dwordx4 v[230:231], off
	v_lshl_add_u64 v[230:231], s[28:29], 0, v[132:133]
	s_mov_b32 m0, s70
	s_nop 0
	global_load_lds_dwordx4 v[230:231], off
	s_waitcnt vmcnt(8)
	s_waitcnt lgkmcnt(0)
	s_barrier
	s_setprio 1
	s_waitcnt lgkmcnt(0)
	v_mfma_f32_16x16x32_bf16 v[126:129], v[146:149], v[178:181], v[126:129]
	v_mfma_f32_16x16x32_bf16 v[126:129], v[150:153], v[182:185], v[126:129]
	v_mfma_f32_16x16x32_bf16 v[118:121], v[154:157], v[178:181], v[118:121]
	v_mfma_f32_16x16x32_bf16 v[118:121], v[158:161], v[182:185], v[118:121]
	v_mfma_f32_16x16x32_bf16 v[110:113], v[146:149], v[186:189], v[110:113]
	v_mfma_f32_16x16x32_bf16 v[110:113], v[150:153], v[190:193], v[110:113]
	v_mfma_f32_16x16x32_bf16 v[102:105], v[154:157], v[186:189], v[102:105]
	v_mfma_f32_16x16x32_bf16 v[102:105], v[158:161], v[190:193], v[102:105]
	v_mfma_f32_16x16x32_bf16 v[92:95], v[146:149], v[194:197], v[92:95]
	v_mfma_f32_16x16x32_bf16 v[92:95], v[150:153], v[200:203], v[92:95]
	v_mfma_f32_16x16x32_bf16 v[84:87], v[154:157], v[194:197], v[84:87]
	v_mfma_f32_16x16x32_bf16 v[84:87], v[158:161], v[200:203], v[84:87]
	v_mfma_f32_16x16x32_bf16 v[76:79], v[146:149], v[206:209], v[76:79]
	v_mfma_f32_16x16x32_bf16 v[76:79], v[150:153], v[210:213], v[76:79]
	v_mfma_f32_16x16x32_bf16 v[68:71], v[154:157], v[206:209], v[68:71]
	v_mfma_f32_16x16x32_bf16 v[68:71], v[158:161], v[210:213], v[68:71]
	s_setprio 0
	s_setprio 1
	v_mfma_f32_16x16x32_bf16 v[122:125], v[162:165], v[178:181], v[122:125]
	v_mfma_f32_16x16x32_bf16 v[122:125], v[166:169], v[182:185], v[122:125]
	v_mfma_f32_16x16x32_bf16 v[114:117], v[170:173], v[178:181], v[114:117]
	v_mfma_f32_16x16x32_bf16 v[114:117], v[174:177], v[182:185], v[114:117]
	v_mfma_f32_16x16x32_bf16 v[106:109], v[162:165], v[186:189], v[106:109]
	v_mfma_f32_16x16x32_bf16 v[106:109], v[166:169], v[190:193], v[106:109]
	v_mfma_f32_16x16x32_bf16 v[98:101], v[170:173], v[186:189], v[98:101]
	v_mfma_f32_16x16x32_bf16 v[98:101], v[174:177], v[190:193], v[98:101]
	v_mfma_f32_16x16x32_bf16 v[88:91], v[162:165], v[194:197], v[88:91]
	v_mfma_f32_16x16x32_bf16 v[88:91], v[166:169], v[200:203], v[88:91]
	v_mfma_f32_16x16x32_bf16 v[80:83], v[170:173], v[194:197], v[80:83]
	v_mfma_f32_16x16x32_bf16 v[80:83], v[174:177], v[200:203], v[80:83]
	v_mfma_f32_16x16x32_bf16 v[72:75], v[162:165], v[206:209], v[72:75]
	v_mfma_f32_16x16x32_bf16 v[72:75], v[166:169], v[210:213], v[72:75]
	s_setprio 2
	s_barrier
; #define PG8_STAGE(bufoff, gbase, voff) do { _Pragma("unroll") for (int _i = 0; _i < 2; ++_i) \
;         __builtin_amdgcn_global_load_lds((const unsigned*)((const char*)(gbase) + (voff)[_i]), (PG8_LAS unsigned*)(lds + (bufoff) + ldsw + _i * 8192), 16, 0, 0); } while (0)
; #define PG8_LDA(dst, b, h) do { _Pragma("unroll") for (int m = 0; m < 4; ++m) _Pragma("unroll") for (int k = 0; k < 2; ++k) dst[m][k] = *(const PG8_LAS bf16x8*)(lds + PG8_SA(b, h) + aoff + m * 2048 + k * 1024); } while (0)
; #define PG8_WAIT_V(n) asm volatile("s_waitcnt vmcnt(" #n ")" ::: "memory")
; #define PG8_WAIT_L(n) asm volatile("s_waitcnt lgkmcnt(" #n ")" ::: "memory")
; #define PG8_BAR __builtin_amdgcn_s_barrier()
; template <class Epi, class Sched, bool ALIGN_EPI = true, bool SP2 = true>
; __device__ __forceinline__ void gemm_phase(PG8_LAS unsigned char* lds, const Gemm g, const Sched& S, const Epi& E, const int tid) {
;     ...
;         for (int t = 0; t < nt; t += 2) {
;             const bool last = (t == nt - 2);
;             const char* a1 = cA + (size_t)(t + 1) * kstep;
;             const char* a2 = last ? nA : cA + (size_t)(t + 2) * kstep; const char* b2 = last ? nB : cB + (size_t)(t + 2) * kstep;
;             const char* a3 = a2 + kstep; const char* b3 = b2 + kstep;
;             if (last && has_next) S.a_ready(nxt);
;             if constexpr (SP2) {
;             PG8_LDB(B0, 0, 0); PG8_LDB(B1, 0, 1); PG8_SCHED; PG8_LDA(At, 0, 0); PG8_STAGE(PG8_SA(1, 1), a1 + hstepA, voffA);
;             PG8_WAIT_V(8); PG8_WAIT_L(0); PG8_BAR; PG8_MMA(0, 0, At, B0); PG8_MMA(0, 1, At, B1); PG8_BAR; PG8_SCHED;
;             PG8_LDA(At, 0, 1); PG8_STAGE(PG8_SB(0, 0), b2, voffB); PG8_STAGE(PG8_SB(0, 1), b2 + hstepB, voffB); PG8_STAGE(PG8_SA(0, 0), a2, voffA);
;             PG8_WAIT_V(8); PG8_WAIT_L(0); PG8_BAR; PG8_MMA(1, 0, At, B0); PG8_MMA(1, 1, At, B1); PG8_BAR; PG8_SCHED;
;             PG8_LDB(B0, 1, 0); PG8_LDB(B1, 1, 1); PG8_SCHED; PG8_LDA(At, 1, 0); PG8_STAGE(PG8_SA(0, 1), a2 + hstepA, voffA);
;             PG8_WAIT_V(8); PG8_WAIT_L(0); PG8_BAR; PG8_MMA(0, 0, At, B0); PG8_MMA(0, 1, At, B1); PG8_BAR; PG8_SCHED;
;             PG8_LDA(At, 1, 1); PG8_STAGE(PG8_SB(1, 0), b3, voffB); PG8_STAGE(PG8_SB(1, 1), b3 + hstepB, voffB); PG8_STAGE(PG8_SA(1, 0), a3, voffA);
;             PG8_WAIT_V(8); PG8_WAIT_L(0); PG8_BAR; PG8_MMA(1, 0, At, B0); PG8_MMA(1, 1, At, B1); PG8_BAR; PG8_SCHED;
	v_mfma_f32_16x16x32_bf16 v[64:67], v[170:173], v[206:209], v[64:67]
	v_mfma_f32_16x16x32_bf16 v[64:67], v[174:177], v[210:213], v[64:67]
	s_setprio 0
	s_add_i32 s28, s30, s21
	v_lshl_add_u64 v[222:223], v[222:223], 0, s[4:5]
	s_mov_b32 m0, s28
	ds_read_b128 v[178:181], v144 offset:49152
	ds_read_b128 v[182:185], v144 offset:50176
	ds_read_b128 v[186:189], v144 offset:51200
	ds_read_b128 v[190:193], v144 offset:52224
	ds_read_b128 v[194:197], v144 offset:53248
	ds_read_b128 v[200:203], v144 offset:54272
	ds_read_b128 v[206:209], v144 offset:55296
	ds_read_b128 v[210:213], v144 offset:56320
	global_load_lds_dwordx4 v[222:223], off
	s_add_i32 m0, s28, 0x2000
	s_add_u32 s28, s64, 0x80080
	v_lshl_add_u64 v[222:223], v[224:225], 0, s[4:5]
	s_addc_u32 s29, s65, 0
	s_add_i32 s30, s31, s21
	global_load_lds_dwordx4 v[222:223], off
	v_lshl_add_u64 v[222:223], s[28:29], 0, v[134:135]
	s_mov_b32 m0, s30
	s_nop 0
	global_load_lds_dwordx4 v[222:223], off
	v_lshl_add_u64 v[222:223], s[28:29], 0, v[130:131]
	s_add_i32 m0, s30, 0x2000
	s_nop 0
	global_load_lds_dwordx4 v[222:223], off
	v_lshl_add_u64 v[222:223], v[226:227], 0, s[4:5]
	s_mov_b32 m0, s71
	s_nop 0
	global_load_lds_dwordx4 v[222:223], off
	v_lshl_add_u64 v[222:223], v[228:229], 0, s[4:5]
	s_mov_b32 m0, s72
	s_nop 0
	global_load_lds_dwordx4 v[222:223], off
	s_waitcnt vmcnt(8)
	s_waitcnt lgkmcnt(0)
	s_barrier
	s_setprio 1
	s_waitcnt lgkmcnt(0)
	v_mfma_f32_16x16x32_bf16 v[60:63], v[146:149], v[178:181], v[60:63]
	v_mfma_f32_16x16x32_bf16 v[60:63], v[150:153], v[182:185], v[60:63]
	v_mfma_f32_16x16x32_bf16 v[52:55], v[154:157], v[178:181], v[52:55]
	v_mfma_f32_16x16x32_bf16 v[52:55], v[158:161], v[182:185], v[52:55]
	v_mfma_f32_16x16x32_bf16 v[44:47], v[146:149], v[186:189], v[44:47]
	v_mfma_f32_16x16x32_bf16 v[44:47], v[150:153], v[190:193], v[44:47]
	v_mfma_f32_16x16x32_bf16 v[36:39], v[154:157], v[186:189], v[36:39]
	v_mfma_f32_16x16x32_bf16 v[36:39], v[158:161], v[190:193], v[36:39]
	v_mfma_f32_16x16x32_bf16 v[28:31], v[146:149], v[194:197], v[28:31]
	v_mfma_f32_16x16x32_bf16 v[28:31], v[150:153], v[200:203], v[28:31]
	v_mfma_f32_16x16x32_bf16 v[20:23], v[154:157], v[194:197], v[20:23]
	v_mfma_f32_16x16x32_bf16 v[20:23], v[158:161], v[200:203], v[20:23]
	v_mfma_f32_16x16x32_bf16 v[12:15], v[146:149], v[206:209], v[12:15]
	v_mfma_f32_16x16x32_bf16 v[12:15], v[150:153], v[210:213], v[12:15]
	v_mfma_f32_16x16x32_bf16 v[4:7], v[154:157], v[206:209], v[4:7]
	v_mfma_f32_16x16x32_bf16 v[4:7], v[158:161], v[210:213], v[4:7]
	s_setprio 0
	s_setprio 1
	v_mfma_f32_16x16x32_bf16 v[56:59], v[162:165], v[178:181], v[56:59]
	v_mfma_f32_16x16x32_bf16 v[56:59], v[166:169], v[182:185], v[56:59]
	v_mfma_f32_16x16x32_bf16 v[48:51], v[170:173], v[178:181], v[48:51]
	v_mfma_f32_16x16x32_bf16 v[48:51], v[174:177], v[182:185], v[48:51]
	v_mfma_f32_16x16x32_bf16 v[40:43], v[162:165], v[186:189], v[40:43]
	v_mfma_f32_16x16x32_bf16 v[40:43], v[166:169], v[190:193], v[40:43]
	v_mfma_f32_16x16x32_bf16 v[32:35], v[170:173], v[186:189], v[32:35]
	v_mfma_f32_16x16x32_bf16 v[32:35], v[174:177], v[190:193], v[32:35]
	v_mfma_f32_16x16x32_bf16 v[24:27], v[162:165], v[194:197], v[24:27]
	v_mfma_f32_16x16x32_bf16 v[24:27], v[166:169], v[200:203], v[24:27]
	v_mfma_f32_16x16x32_bf16 v[16:19], v[170:173], v[194:197], v[16:19]
	v_mfma_f32_16x16x32_bf16 v[16:19], v[174:177], v[200:203], v[16:19]
	v_mfma_f32_16x16x32_bf16 v[8:11], v[162:165], v[206:209], v[8:11]
	v_mfma_f32_16x16x32_bf16 v[8:11], v[166:169], v[210:213], v[8:11]
	s_setprio 2
	s_barrier
	v_mfma_f32_16x16x32_bf16 v[0:3], v[170:173], v[206:209], v[0:3]
	v_mfma_f32_16x16x32_bf16 v[0:3], v[174:177], v[210:213], v[0:3]
	s_setprio 0
	s_add_i32 s52, s52, 2
	s_add_u32 s62, s62, 0x100
	s_addc_u32 s63, s63, 0
	s_add_u32 s49, s49, 0x100
	s_addc_u32 s51, s51, 0
	s_cmp_gt_u32 s52, 29
	s_cbranch_scc0 .LBB0_1319
	s_and_b64 vcc, exec, s[46:47]
	s_cbranch_vccz .LBB0_1322
	s_barrier

; #define PG8_STAGE(bufoff, gbase, voff) do { _Pragma("unroll") for (int _i = 0; _i < 2; ++_i) \
;         __builtin_amdgcn_global_load_lds((const unsigned*)((const char*)(gbase) + (voff)[_i]), (PG8_LAS unsigned*)(lds + (bufoff) + ldsw + _i * 8192), 16, 0, 0); } while (0)
; #define PG8_LDA(dst, b, h) do { _Pragma("unroll") for (int m = 0; m < 4; ++m) _Pragma("unroll") for (int k = 0; k < 2; ++k) dst[m][k] = *(const PG8_LAS bf16x8*)(lds + PG8_SA(b, h) + aoff + m * 2048 + k * 1024); } while (0)
; #define PG8_WAIT_V(n) asm volatile("s_waitcnt vmcnt(" #n ")" ::: "memory")
; #define PG8_WAIT_L(n) asm volatile("s_waitcnt lgkmcnt(" #n ")" ::: "memory")
; #define PG8_BAR __builtin_amdgcn_s_barrier()
; template <class Epi, class Sched, bool ALIGN_EPI = true, bool SP2 = true>
; __device__ __forceinline__ void gemm_phase(PG8_LAS unsigned char* lds, const Gemm g, const Sched& S, const Epi& E, const int tid) {
;     ...
;         for (int t = 0; t < nt; t += 2) {
;             const bool last = (t == nt - 2);
;             const char* a1 = cA + (size_t)(t + 1) * kstep;
;             const char* a2 = last ? nA : cA + (size_t)(t + 2) * kstep; const char* b2 = last ? nB : cB + (size_t)(t + 2) * kstep;
;             const char* a3 = a2 + kstep; const char* b3 = b2 + kstep;
;             if (last && has_next) S.a_ready(nxt);
;             if constexpr (SP2) {
;             PG8_LDB(B0, 0, 0); PG8_LDB(B1, 0, 1); PG8_SCHED; PG8_LDA(At, 0, 0); PG8_STAGE(PG8_SA(1, 1), a1 + hstepA, voffA);
;             PG8_WAIT_V(8); PG8_WAIT_L(0); PG8_BAR; PG8_MMA(0, 0, At, B0); PG8_MMA(0, 1, At, B1); PG8_BAR; PG8_SCHED;
;             PG8_LDA(At, 0, 1); PG8_STAGE(PG8_SB(0, 0), b2, voffB); PG8_STAGE(PG8_SB(0, 1), b2 + hstepB, voffB); PG8_STAGE(PG8_SA(0, 0), a2, voffA);
;             PG8_WAIT_V(8); PG8_WAIT_L(0); PG8_BAR; PG8_MMA(1, 0, At, B0); PG8_MMA(1, 1, At, B1); PG8_BAR; PG8_SCHED;
;             PG8_LDB(B0, 1, 0); PG8_LDB(B1, 1, 1); PG8_SCHED; PG8_LDA(At, 1, 0); PG8_STAGE(PG8_SA(0, 1), a2 + hstepA, voffA);
;             PG8_WAIT_V(8); PG8_WAIT_L(0); PG8_BAR; PG8_MMA(0, 0, At, B0); PG8_MMA(0, 1, At, B1); PG8_BAR; PG8_SCHED;
;             PG8_LDA(At, 1, 1); PG8_STAGE(PG8_SB(1, 0), b3, voffB); PG8_STAGE(PG8_SB(1, 1), b3 + hstepB, voffB); PG8_STAGE(PG8_SA(1, 0), a3, voffA);
;             PG8_WAIT_V(8); PG8_WAIT_L(0); PG8_BAR; PG8_MMA(1, 0, At, B0); PG8_MMA(1, 1, At, B1); PG8_BAR; PG8_SCHED;
.LBB0_1523:
	s_add_i32 vcc_lo, s72, 2
	s_add_u32 s70, s82, 0x100
	s_addc_u32 s71, s83, 0
	s_add_i32 s30, 0, 0x10000
	s_cmp_eq_u32 s29, s72
	s_cselect_b32 s81, s63, s71
	s_cselect_b32 s80, s62, s70
	v_add_u32_e32 v96, s30, v141
	s_cselect_b32 s73, s65, s59
	s_cselect_b32 s72, s64, s57
	s_add_i32 s31, 0, 0x14000
	ds_read_b128 v[146:149], v96
	ds_read_b128 v[150:153], v96 offset:1024
	ds_read_b128 v[154:157], v96 offset:2048
	ds_read_b128 v[158:161], v96 offset:3072
	v_add_u32_e32 v96, s31, v141
	ds_read_b128 v[162:165], v96
	ds_read_b128 v[166:169], v96 offset:1024
	ds_read_b128 v[170:173], v96 offset:2048
	ds_read_b128 v[174:177], v96 offset:3072
	v_lshl_add_u64 v[98:99], s[82:83], 0, v[136:137]
	s_add_i32 m0, s23, 0xc000
	ds_read_b128 v[178:181], v145
	ds_read_b128 v[182:185], v145 offset:1024
	ds_read_b128 v[186:189], v145 offset:2048
	ds_read_b128 v[190:193], v145 offset:3072
	ds_read_b128 v[194:197], v145 offset:4096
	ds_read_b128 v[200:203], v145 offset:5120
	ds_read_b128 v[206:209], v145 offset:6144
	ds_read_b128 v[210:213], v145 offset:7168
	global_load_lds_dwordx4 v[98:99], off
	v_lshl_add_u64 v[98:99], s[82:83], 0, v[138:139]
	s_add_i32 m0, s23, 0xe000
	s_nop 0
	global_load_lds_dwordx4 v[98:99], off
	s_waitcnt vmcnt(8)
	s_waitcnt lgkmcnt(0)
	s_barrier
	s_setprio 1
	s_waitcnt lgkmcnt(0)
	v_mfma_f32_16x16x32_bf16 v[52:55], v[146:149], v[178:181], v[52:55]
	v_mfma_f32_16x16x32_bf16 v[56:59], v[154:157], v[178:181], v[56:59]
	v_mfma_f32_16x16x32_bf16 v[104:107], v[146:149], v[186:189], v[104:107]
	v_mfma_f32_16x16x32_bf16 v[84:87], v[154:157], v[186:189], v[84:87]
	v_mfma_f32_16x16x32_bf16 v[110:113], v[146:149], v[194:197], v[110:113]
	v_mfma_f32_16x16x32_bf16 v[98:101], v[154:157], v[194:197], v[100:103]
	v_mfma_f32_16x16x32_bf16 v[88:91], v[146:149], v[206:209], v[88:91]
	v_mfma_f32_16x16x32_bf16 v[80:83], v[154:157], v[206:209], v[80:83]
	v_mfma_f32_16x16x32_bf16 v[52:55], v[150:153], v[182:185], v[52:55]
	v_mfma_f32_16x16x32_bf16 v[56:59], v[158:161], v[182:185], v[56:59]
	v_mfma_f32_16x16x32_bf16 v[104:107], v[150:153], v[190:193], v[104:107]
	v_mfma_f32_16x16x32_bf16 v[84:87], v[158:161], v[190:193], v[84:87]
	v_mfma_f32_16x16x32_bf16 v[110:113], v[150:153], v[200:203], v[110:113]
	v_mfma_f32_16x16x32_bf16 v[98:101], v[158:161], v[200:203], v[98:101]
	v_mfma_f32_16x16x32_bf16 v[88:91], v[150:153], v[210:213], v[88:91]
	v_mfma_f32_16x16x32_bf16 v[80:83], v[158:161], v[210:213], v[80:83]
	s_setprio 0
	s_setprio 1
	v_mfma_f32_16x16x32_bf16 v[48:51], v[162:165], v[178:181], v[48:51]
	v_mfma_f32_16x16x32_bf16 v[44:47], v[170:173], v[178:181], v[44:47]
	v_mfma_f32_16x16x32_bf16 v[76:79], v[162:165], v[186:189], v[76:79]
	v_mfma_f32_16x16x32_bf16 v[68:71], v[170:173], v[186:189], v[68:71]
	v_mfma_f32_16x16x32_bf16 v[130:133], v[162:165], v[194:197], v[130:133]
	v_mfma_f32_16x16x32_bf16 v[92:95], v[170:173], v[194:197], v[92:95]
	v_mfma_f32_16x16x32_bf16 v[72:75], v[162:165], v[206:209], v[72:75]
	v_mfma_f32_16x16x32_bf16 v[64:67], v[170:173], v[206:209], v[64:67]
	v_mfma_f32_16x16x32_bf16 v[48:51], v[166:169], v[182:185], v[48:51]
	v_mfma_f32_16x16x32_bf16 v[44:47], v[174:177], v[182:185], v[44:47]
	v_mfma_f32_16x16x32_bf16 v[76:79], v[166:169], v[190:193], v[76:79]
	v_mfma_f32_16x16x32_bf16 v[68:71], v[174:177], v[190:193], v[68:71]
	v_mfma_f32_16x16x32_bf16 v[130:133], v[166:169], v[200:203], v[130:133]
	v_mfma_f32_16x16x32_bf16 v[92:95], v[174:177], v[200:203], v[92:95]
	s_setprio 2
	s_barrier
	v_mfma_f32_16x16x32_bf16 v[72:75], v[166:169], v[210:213], v[72:75]
	v_mfma_f32_16x16x32_bf16 v[64:67], v[174:177], v[210:213], v[64:67]
	s_setprio 0
	s_add_i32 s30, s30, s22
	v_lshl_add_u64 v[224:225], s[72:73], 0, v[108:109]
	s_mov_b32 m0, s30
	ds_read_b128 v[178:181], v145 offset:16384
	ds_read_b128 v[182:185], v145 offset:17408
	ds_read_b128 v[186:189], v145 offset:18432
	ds_read_b128 v[190:193], v145 offset:19456
	ds_read_b128 v[194:197], v145 offset:20480
	ds_read_b128 v[200:203], v145 offset:21504
	ds_read_b128 v[206:209], v145 offset:22528
	ds_read_b128 v[210:213], v145 offset:23552
	global_load_lds_dwordx4 v[224:225], off
	s_add_i32 m0, s30, 0x2000
	s_add_u32 s82, s72, 0x160000
	v_lshl_add_u64 v[226:227], s[72:73], 0, v[134:135]
	s_addc_u32 s83, s73, 0
	s_add_i32 s30, s31, s22
	global_load_lds_dwordx4 v[226:227], off
	v_lshl_add_u64 v[102:103], s[82:83], 0, v[108:109]
	s_mov_b32 m0, s30
	v_lshl_add_u64 v[228:229], s[80:81], 0, v[108:109]
	global_load_lds_dwordx4 v[102:103], off
	v_lshl_add_u64 v[102:103], s[82:83], 0, v[134:135]
	s_add_i32 m0, s30, 0x2000
	v_lshl_add_u64 v[230:231], s[80:81], 0, v[134:135]
	global_load_lds_dwordx4 v[102:103], off
	s_mov_b32 m0, s23
	s_nop 0
	global_load_lds_dwordx4 v[228:229], off
	s_mov_b32 m0, s24
	s_nop 0
	global_load_lds_dwordx4 v[230:231], off
	s_waitcnt vmcnt(8)
	s_waitcnt lgkmcnt(0)
	s_barrier
; #define PG8_STAGE(bufoff, gbase, voff) do { _Pragma("unroll") for (int _i = 0; _i < 2; ++_i) \
;         __builtin_amdgcn_global_load_lds((const unsigned*)((const char*)(gbase) + (voff)[_i]), (PG8_LAS unsigned*)(lds + (bufoff) + ldsw + _i * 8192), 16, 0, 0); } while (0)
; #define PG8_LDA(dst, b, h) do { _Pragma("unroll") for (int m = 0; m < 4; ++m) _Pragma("unroll") for (int k = 0; k < 2; ++k) dst[m][k] = *(const PG8_LAS bf16x8*)(lds + PG8_SA(b, h) + aoff + m * 2048 + k * 1024); } while (0)
; #define PG8_WAIT_V(n) asm volatile("s_waitcnt vmcnt(" #n ")" ::: "memory")
; #define PG8_WAIT_L(n) asm volatile("s_waitcnt lgkmcnt(" #n ")" ::: "memory")
; #define PG8_BAR __builtin_amdgcn_s_barrier()
; template <class Epi, class Sched, bool ALIGN_EPI = true, bool SP2 = true>
; __device__ __forceinline__ void gemm_phase(PG8_LAS unsigned char* lds, const Gemm g, const Sched& S, const Epi& E, const int tid) {
;     ...
;         for (int t = 0; t < nt; t += 2) {
;             const bool last = (t == nt - 2);
;             const char* a1 = cA + (size_t)(t + 1) * kstep;
;             const char* a2 = last ? nA : cA + (size_t)(t + 2) * kstep; const char* b2 = last ? nB : cB + (size_t)(t + 2) * kstep;
;             const char* a3 = a2 + kstep; const char* b3 = b2 + kstep;
;             if (last && has_next) S.a_ready(nxt);
;             if constexpr (SP2) {
;             PG8_LDB(B0, 0, 0); PG8_LDB(B1, 0, 1); PG8_SCHED; PG8_LDA(At, 0, 0); PG8_STAGE(PG8_SA(1, 1), a1 + hstepA, voffA);
;             PG8_WAIT_V(8); PG8_WAIT_L(0); PG8_BAR; PG8_MMA(0, 0, At, B0); PG8_MMA(0, 1, At, B1); PG8_BAR; PG8_SCHED;
;             PG8_LDA(At, 0, 1); PG8_STAGE(PG8_SB(0, 0), b2, voffB); PG8_STAGE(PG8_SB(0, 1), b2 + hstepB, voffB); PG8_STAGE(PG8_SA(0, 0), a2, voffA);
;             PG8_WAIT_V(8); PG8_WAIT_L(0); PG8_BAR; PG8_MMA(1, 0, At, B0); PG8_MMA(1, 1, At, B1); PG8_BAR; PG8_SCHED;
;             PG8_LDB(B0, 1, 0); PG8_LDB(B1, 1, 1); PG8_SCHED; PG8_LDA(At, 1, 0); PG8_STAGE(PG8_SA(0, 1), a2 + hstepA, voffA);
;             PG8_WAIT_V(8); PG8_WAIT_L(0); PG8_BAR; PG8_MMA(0, 0, At, B0); PG8_MMA(0, 1, At, B1); PG8_BAR; PG8_SCHED;
;             PG8_LDA(At, 1, 1); PG8_STAGE(PG8_SB(1, 0), b3, voffB); PG8_STAGE(PG8_SB(1, 1), b3 + hstepB, voffB); PG8_STAGE(PG8_SA(1, 0), a3, voffA);
;             PG8_WAIT_V(8); PG8_WAIT_L(0); PG8_BAR; PG8_MMA(1, 0, At, B0); PG8_MMA(1, 1, At, B1); PG8_BAR; PG8_SCHED;
	s_setprio 1
	s_waitcnt lgkmcnt(0)
	v_mfma_f32_16x16x32_bf16 v[126:129], v[146:149], v[178:181], v[126:129]
	v_mfma_f32_16x16x32_bf16 v[122:125], v[154:157], v[178:181], v[122:125]
	v_mfma_f32_16x16x32_bf16 v[60:63], v[146:149], v[186:189], v[60:63]
	v_mfma_f32_16x16x32_bf16 v[40:43], v[154:157], v[186:189], v[40:43]
	v_mfma_f32_16x16x32_bf16 v[28:31], v[146:149], v[194:197], v[28:31]
	v_mfma_f32_16x16x32_bf16 v[24:27], v[154:157], v[194:197], v[24:27]
	v_mfma_f32_16x16x32_bf16 v[12:15], v[146:149], v[206:209], v[12:15]
	v_mfma_f32_16x16x32_bf16 v[8:11], v[154:157], v[206:209], v[8:11]
	v_mfma_f32_16x16x32_bf16 v[126:129], v[150:153], v[182:185], v[126:129]
	v_mfma_f32_16x16x32_bf16 v[122:125], v[158:161], v[182:185], v[122:125]
	v_mfma_f32_16x16x32_bf16 v[60:63], v[150:153], v[190:193], v[60:63]
	v_mfma_f32_16x16x32_bf16 v[40:43], v[158:161], v[190:193], v[40:43]
	v_mfma_f32_16x16x32_bf16 v[28:31], v[150:153], v[200:203], v[28:31]
	v_mfma_f32_16x16x32_bf16 v[24:27], v[158:161], v[200:203], v[24:27]
	v_mfma_f32_16x16x32_bf16 v[12:15], v[150:153], v[210:213], v[12:15]
	v_mfma_f32_16x16x32_bf16 v[8:11], v[158:161], v[210:213], v[8:11]
	s_setprio 0
	s_setprio 1
	v_mfma_f32_16x16x32_bf16 v[118:121], v[162:165], v[178:181], v[118:121]
	v_mfma_f32_16x16x32_bf16 v[114:117], v[170:173], v[178:181], v[114:117]
	v_mfma_f32_16x16x32_bf16 v[36:39], v[162:165], v[186:189], v[36:39]
	v_mfma_f32_16x16x32_bf16 v[32:35], v[170:173], v[186:189], v[32:35]
	v_mfma_f32_16x16x32_bf16 v[20:23], v[162:165], v[194:197], v[20:23]
	v_mfma_f32_16x16x32_bf16 v[16:19], v[170:173], v[194:197], v[16:19]
	v_mfma_f32_16x16x32_bf16 v[4:7], v[162:165], v[206:209], v[4:7]
	v_mfma_f32_16x16x32_bf16 v[0:3], v[170:173], v[206:209], v[0:3]
	v_mfma_f32_16x16x32_bf16 v[118:121], v[166:169], v[182:185], v[118:121]
	v_mfma_f32_16x16x32_bf16 v[114:117], v[174:177], v[182:185], v[114:117]
	v_mfma_f32_16x16x32_bf16 v[36:39], v[166:169], v[190:193], v[36:39]
	v_mfma_f32_16x16x32_bf16 v[32:35], v[174:177], v[190:193], v[32:35]
	v_mfma_f32_16x16x32_bf16 v[20:23], v[166:169], v[200:203], v[20:23]
	v_mfma_f32_16x16x32_bf16 v[16:19], v[174:177], v[200:203], v[16:19]
	s_setprio 2
	s_barrier
	v_mfma_f32_16x16x32_bf16 v[4:7], v[166:169], v[210:213], v[4:7]
	v_mfma_f32_16x16x32_bf16 v[0:3], v[174:177], v[210:213], v[0:3]
	s_setprio 0
	s_add_i32 s30, 0, 0x18000
	v_add_u32_e32 v96, s30, v141
	s_add_i32 s31, 0, 0x1c000
	ds_read_b128 v[146:149], v96
	ds_read_b128 v[150:153], v96 offset:1024
	ds_read_b128 v[154:157], v96 offset:2048
	ds_read_b128 v[158:161], v96 offset:3072
	v_add_u32_e32 v96, s31, v141
	ds_read_b128 v[162:165], v96
	ds_read_b128 v[166:169], v96 offset:1024
	ds_read_b128 v[170:173], v96 offset:2048
	ds_read_b128 v[174:177], v96 offset:3072
	s_add_u32 s80, s80, 0x160000
	s_addc_u32 s81, s81, 0
	s_mov_b32 m0, s25
	v_lshl_add_u64 v[102:103], s[80:81], 0, v[108:109]
	ds_read_b128 v[178:181], v145 offset:32768
	ds_read_b128 v[182:185], v145 offset:33792
	ds_read_b128 v[186:189], v145 offset:34816
	ds_read_b128 v[190:193], v145 offset:35840
	ds_read_b128 v[194:197], v145 offset:36864
	ds_read_b128 v[200:203], v145 offset:37888
	ds_read_b128 v[206:209], v145 offset:38912
	ds_read_b128 v[210:213], v145 offset:39936
	global_load_lds_dwordx4 v[102:103], off
	v_lshl_add_u64 v[102:103], s[80:81], 0, v[134:135]
	s_mov_b32 m0, s49
	s_nop 0
	global_load_lds_dwordx4 v[102:103], off
	s_waitcnt vmcnt(8)
	s_waitcnt lgkmcnt(0)
	s_barrier
	s_setprio 1
	s_waitcnt lgkmcnt(0)
	v_mfma_f32_16x16x32_bf16 v[52:55], v[146:149], v[178:181], v[52:55]
	v_mfma_f32_16x16x32_bf16 v[56:59], v[154:157], v[178:181], v[56:59]
	v_mfma_f32_16x16x32_bf16 v[102:105], v[146:149], v[186:189], v[104:107]
	v_mfma_f32_16x16x32_bf16 v[84:87], v[154:157], v[186:189], v[84:87]
	v_mfma_f32_16x16x32_bf16 v[110:113], v[146:149], v[194:197], v[110:113]
	v_mfma_f32_16x16x32_bf16 v[98:101], v[154:157], v[194:197], v[98:101]
	v_mfma_f32_16x16x32_bf16 v[88:91], v[146:149], v[206:209], v[88:91]
	v_mfma_f32_16x16x32_bf16 v[80:83], v[154:157], v[206:209], v[80:83]
	v_mfma_f32_16x16x32_bf16 v[52:55], v[150:153], v[182:185], v[52:55]
	v_mfma_f32_16x16x32_bf16 v[56:59], v[158:161], v[182:185], v[56:59]
	v_mfma_f32_16x16x32_bf16 v[104:107], v[150:153], v[190:193], v[102:105]
	v_mfma_f32_16x16x32_bf16 v[84:87], v[158:161], v[190:193], v[84:87]
	v_mfma_f32_16x16x32_bf16 v[110:113], v[150:153], v[200:203], v[110:113]
	v_mfma_f32_16x16x32_bf16 v[100:103], v[158:161], v[200:203], v[98:101]
	v_mfma_f32_16x16x32_bf16 v[88:91], v[150:153], v[210:213], v[88:91]
	v_mfma_f32_16x16x32_bf16 v[80:83], v[158:161], v[210:213], v[80:83]
	s_setprio 0
	s_setprio 1
	v_mfma_f32_16x16x32_bf16 v[48:51], v[162:165], v[178:181], v[48:51]
	v_mfma_f32_16x16x32_bf16 v[44:47], v[170:173], v[178:181], v[44:47]
	v_mfma_f32_16x16x32_bf16 v[76:79], v[162:165], v[186:189], v[76:79]
	v_mfma_f32_16x16x32_bf16 v[68:71], v[170:173], v[186:189], v[68:71]
	v_mfma_f32_16x16x32_bf16 v[130:133], v[162:165], v[194:197], v[130:133]
	v_mfma_f32_16x16x32_bf16 v[92:95], v[170:173], v[194:197], v[92:95]
	v_mfma_f32_16x16x32_bf16 v[72:75], v[162:165], v[206:209], v[72:75]
	v_mfma_f32_16x16x32_bf16 v[64:67], v[170:173], v[206:209], v[64:67]
	v_mfma_f32_16x16x32_bf16 v[48:51], v[166:169], v[182:185], v[48:51]
	v_mfma_f32_16x16x32_bf16 v[44:47], v[174:177], v[182:185], v[44:47]
	v_mfma_f32_16x16x32_bf16 v[76:79], v[166:169], v[190:193], v[76:79]
	v_mfma_f32_16x16x32_bf16 v[68:71], v[174:177], v[190:193], v[68:71]
	v_mfma_f32_16x16x32_bf16 v[130:133], v[166:169], v[200:203], v[130:133]
	v_mfma_f32_16x16x32_bf16 v[92:95], v[174:177], v[200:203], v[92:95]
	s_setprio 2
	s_barrier
; #define PG8_STAGE(bufoff, gbase, voff) do { _Pragma("unroll") for (int _i = 0; _i < 2; ++_i) \
;         __builtin_amdgcn_global_load_lds((const unsigned*)((const char*)(gbase) + (voff)[_i]), (PG8_LAS unsigned*)(lds + (bufoff) + ldsw + _i * 8192), 16, 0, 0); } while (0)
; #define PG8_LDA(dst, b, h) do { _Pragma("unroll") for (int m = 0; m < 4; ++m) _Pragma("unroll") for (int k = 0; k < 2; ++k) dst[m][k] = *(const PG8_LAS bf16x8*)(lds + PG8_SA(b, h) + aoff + m * 2048 + k * 1024); } while (0)
; #define PG8_WAIT_V(n) asm volatile("s_waitcnt vmcnt(" #n ")" ::: "memory")
; #define PG8_WAIT_L(n) asm volatile("s_waitcnt lgkmcnt(" #n ")" ::: "memory")
; #define PG8_BAR __builtin_amdgcn_s_barrier()
; template <class Epi, class Sched, bool ALIGN_EPI = true, bool SP2 = true>
; __device__ __forceinline__ void gemm_phase(PG8_LAS unsigned char* lds, const Gemm g, const Sched& S, const Epi& E, const int tid) {
;     ...
;         for (int t = 0; t < nt; t += 2) {
;             const bool last = (t == nt - 2);
;             const char* a1 = cA + (size_t)(t + 1) * kstep;
;             const char* a2 = last ? nA : cA + (size_t)(t + 2) * kstep; const char* b2 = last ? nB : cB + (size_t)(t + 2) * kstep;
;             const char* a3 = a2 + kstep; const char* b3 = b2 + kstep;
;             if (last && has_next) S.a_ready(nxt);
;             if constexpr (SP2) {
;             PG8_LDB(B0, 0, 0); PG8_LDB(B1, 0, 1); PG8_SCHED; PG8_LDA(At, 0, 0); PG8_STAGE(PG8_SA(1, 1), a1 + hstepA, voffA);
;             PG8_WAIT_V(8); PG8_WAIT_L(0); PG8_BAR; PG8_MMA(0, 0, At, B0); PG8_MMA(0, 1, At, B1); PG8_BAR; PG8_SCHED;
;             PG8_LDA(At, 0, 1); PG8_STAGE(PG8_SB(0, 0), b2, voffB); PG8_STAGE(PG8_SB(0, 1), b2 + hstepB, voffB); PG8_STAGE(PG8_SA(0, 0), a2, voffA);
;             PG8_WAIT_V(8); PG8_WAIT_L(0); PG8_BAR; PG8_MMA(1, 0, At, B0); PG8_MMA(1, 1, At, B1); PG8_BAR; PG8_SCHED;
;             PG8_LDB(B0, 1, 0); PG8_LDB(B1, 1, 1); PG8_SCHED; PG8_LDA(At, 1, 0); PG8_STAGE(PG8_SA(0, 1), a2 + hstepA, voffA);
;             PG8_WAIT_V(8); PG8_WAIT_L(0); PG8_BAR; PG8_MMA(0, 0, At, B0); PG8_MMA(0, 1, At, B1); PG8_BAR; PG8_SCHED;
;             PG8_LDA(At, 1, 1); PG8_STAGE(PG8_SB(1, 0), b3, voffB); PG8_STAGE(PG8_SB(1, 1), b3 + hstepB, voffB); PG8_STAGE(PG8_SA(1, 0), a3, voffA);
;             PG8_WAIT_V(8); PG8_WAIT_L(0); PG8_BAR; PG8_MMA(1, 0, At, B0); PG8_MMA(1, 1, At, B1); PG8_BAR; PG8_SCHED;
	v_mfma_f32_16x16x32_bf16 v[72:75], v[166:169], v[210:213], v[72:75]
	v_mfma_f32_16x16x32_bf16 v[64:67], v[174:177], v[210:213], v[64:67]
	s_setprio 0
	s_add_i32 s30, s30, s22
	v_lshl_add_u64 v[98:99], v[224:225], 0, s[4:5]
	s_mov_b32 m0, s30
	ds_read_b128 v[178:181], v145 offset:49152
	ds_read_b128 v[182:185], v145 offset:50176
	ds_read_b128 v[186:189], v145 offset:51200
	ds_read_b128 v[190:193], v145 offset:52224
	ds_read_b128 v[194:197], v145 offset:53248
	ds_read_b128 v[200:203], v145 offset:54272
	ds_read_b128 v[206:209], v145 offset:55296
	ds_read_b128 v[210:213], v145 offset:56320
	global_load_lds_dwordx4 v[98:99], off
	s_add_i32 m0, s30, 0x2000
	s_add_u32 s72, s72, 0x160080
	v_lshl_add_u64 v[98:99], v[226:227], 0, s[4:5]
	s_addc_u32 s73, s73, 0
	s_add_i32 s30, s31, s22
	global_load_lds_dwordx4 v[98:99], off
	v_lshl_add_u64 v[98:99], s[72:73], 0, v[108:109]
	s_mov_b32 m0, s30
	s_nop 0
	global_load_lds_dwordx4 v[98:99], off
	v_lshl_add_u64 v[98:99], s[72:73], 0, v[134:135]
	s_add_i32 m0, s30, 0x2000
	s_nop 0
	global_load_lds_dwordx4 v[98:99], off
	v_lshl_add_u64 v[98:99], v[228:229], 0, s[4:5]
	s_mov_b32 m0, s91
	s_nop 0
	global_load_lds_dwordx4 v[98:99], off
	v_lshl_add_u64 v[98:99], v[230:231], 0, s[4:5]
	s_mov_b32 m0, s86
	s_nop 0
	global_load_lds_dwordx4 v[98:99], off
	s_waitcnt vmcnt(8)
	s_waitcnt lgkmcnt(0)
	s_barrier
	s_setprio 1
	s_waitcnt lgkmcnt(0)
	v_mfma_f32_16x16x32_bf16 v[126:129], v[146:149], v[178:181], v[126:129]
	v_mfma_f32_16x16x32_bf16 v[122:125], v[154:157], v[178:181], v[122:125]
	v_mfma_f32_16x16x32_bf16 v[60:63], v[146:149], v[186:189], v[60:63]
	v_mfma_f32_16x16x32_bf16 v[40:43], v[154:157], v[186:189], v[40:43]
	v_mfma_f32_16x16x32_bf16 v[28:31], v[146:149], v[194:197], v[28:31]
	v_mfma_f32_16x16x32_bf16 v[24:27], v[154:157], v[194:197], v[24:27]
	v_mfma_f32_16x16x32_bf16 v[12:15], v[146:149], v[206:209], v[12:15]
	v_mfma_f32_16x16x32_bf16 v[8:11], v[154:157], v[206:209], v[8:11]
	v_mfma_f32_16x16x32_bf16 v[126:129], v[150:153], v[182:185], v[126:129]
	v_mfma_f32_16x16x32_bf16 v[122:125], v[158:161], v[182:185], v[122:125]
	v_mfma_f32_16x16x32_bf16 v[60:63], v[150:153], v[190:193], v[60:63]
	v_mfma_f32_16x16x32_bf16 v[40:43], v[158:161], v[190:193], v[40:43]
	v_mfma_f32_16x16x32_bf16 v[28:31], v[150:153], v[200:203], v[28:31]
	v_mfma_f32_16x16x32_bf16 v[24:27], v[158:161], v[200:203], v[24:27]
	v_mfma_f32_16x16x32_bf16 v[12:15], v[150:153], v[210:213], v[12:15]
	v_mfma_f32_16x16x32_bf16 v[8:11], v[158:161], v[210:213], v[8:11]
	s_setprio 0
	s_setprio 1
	v_mfma_f32_16x16x32_bf16 v[118:121], v[162:165], v[178:181], v[118:121]
	v_mfma_f32_16x16x32_bf16 v[114:117], v[170:173], v[178:181], v[114:117]
	v_mfma_f32_16x16x32_bf16 v[36:39], v[162:165], v[186:189], v[36:39]
	v_mfma_f32_16x16x32_bf16 v[32:35], v[170:173], v[186:189], v[32:35]
	v_mfma_f32_16x16x32_bf16 v[20:23], v[162:165], v[194:197], v[20:23]
	v_mfma_f32_16x16x32_bf16 v[16:19], v[170:173], v[194:197], v[16:19]
	v_mfma_f32_16x16x32_bf16 v[4:7], v[162:165], v[206:209], v[4:7]
	v_mfma_f32_16x16x32_bf16 v[0:3], v[170:173], v[206:209], v[0:3]
	v_mfma_f32_16x16x32_bf16 v[118:121], v[166:169], v[182:185], v[118:121]
	v_mfma_f32_16x16x32_bf16 v[114:117], v[174:177], v[182:185], v[114:117]
	v_mfma_f32_16x16x32_bf16 v[36:39], v[166:169], v[190:193], v[36:39]
	v_mfma_f32_16x16x32_bf16 v[32:35], v[174:177], v[190:193], v[32:35]
	v_mfma_f32_16x16x32_bf16 v[20:23], v[166:169], v[200:203], v[20:23]
	v_mfma_f32_16x16x32_bf16 v[16:19], v[174:177], v[200:203], v[16:19]
	s_setprio 2
	s_barrier
	v_mfma_f32_16x16x32_bf16 v[4:7], v[166:169], v[210:213], v[4:7]
	v_mfma_f32_16x16x32_bf16 v[0:3], v[174:177], v[210:213], v[0:3]
	s_setprio 0
	s_add_u32 s57, s57, 0x100
	s_addc_u32 s59, s59, 0
	s_cmp_ge_i32 vcc_lo, s53
	s_mov_b64 s[82:83], s[70:71]
	s_mov_b32 s72, vcc_lo
	s_cbranch_scc0 .LBB0_1523
